# phase 13: GLU epilogue's bias and 12 of 15 y-tile loads issued up front (was 16 serialized load/wait rounds); neighbourhood-attention bias values read from LDS 8 at a time with one wait
# speedup vs baseline: 1.0059x; 1.0030x over previous
.LBB0_1431:
	v_lshl_add_u32 v146, s1, 8, v154
	v_ashrrev_i32_e32 v147, 31, v146
	v_lshl_add_u64 v[144:145], v[146:147], 2, s[12:13]
	flat_load_dwordx4 v[158:161], v[144:145]
	flat_load_dwordx4 v[162:165], v[144:145] offset:16
	v_lshl_add_u32 v148, s0, 8, v152
	v_ashrrev_i32_e32 v149, 31, v148
	v_lshlrev_b64 v[150:151], 10, v[148:149]
	v_lshlrev_b64 v[146:147], 1, v[146:147]
	v_lshl_add_u64 v[150:151], s[60:61], 0, v[150:151]
	v_lshl_add_u64 v[150:151], v[150:151], 0, v[146:147]
	global_load_dwordx4 v[166:169], v[150:151], off
	global_load_dwordx4 v[224:227], v[144:145], off
	global_load_dwordx4 v[228:231], v[144:145], off offset:16
	global_load_dwordx4 v[232:235], v[144:145], off offset:512
	global_load_dwordx4 v[236:239], v[144:145], off offset:528
	global_load_dwordx4 v[170:173], v[150:151], off offset:256
	s_mov_b64 s[98:99], 0x4000
	v_lshl_add_u64 v[244:245], v[150:151], 0, s[98:99]
	global_load_dwordx4 v[174:177], v[244:245], off
	global_load_dwordx4 v[178:181], v[244:245], off offset:256
	s_mov_b64 s[98:99], 0x8000
	v_lshl_add_u64 v[214:215], v[150:151], 0, s[98:99]
	global_load_dwordx4 v[182:185], v[214:215], off
	global_load_dwordx4 v[186:189], v[214:215], off offset:256
	s_mov_b64 s[98:99], 0xc000
	v_lshl_add_u64 v[244:245], v[150:151], 0, s[98:99]
	global_load_dwordx4 v[190:193], v[244:245], off
	global_load_dwordx4 v[194:197], v[244:245], off offset:256
	s_mov_b64 s[98:99], 0x20000
	v_lshl_add_u64 v[214:215], v[150:151], 0, s[98:99]
	global_load_dwordx4 v[198:201], v[214:215], off
	global_load_dwordx4 v[202:205], v[214:215], off offset:256
	s_mov_b64 s[98:99], 0x24000
	v_lshl_add_u64 v[244:245], v[150:151], 0, s[98:99]
	global_load_dwordx4 v[206:209], v[244:245], off
	global_load_dwordx4 v[210:213], v[244:245], off offset:256
	s_mov_b64 s[98:99], 0x28000
	v_lshl_add_u64 v[214:215], v[150:151], 0, s[98:99]
	global_load_dwordx4 v[240:243], v[214:215], off
	s_waitcnt vmcnt(0) lgkmcnt(0)
	v_add_f32_e32 v124, v124, v158
	v_add_f32_e32 v120, v120, v162
	v_mul_f32_e32 v124, 0xbfb8aa3b, v124
	v_add_f32_e32 v125, v125, v159
	v_add_f32_e32 v126, v126, v160
	v_mul_f32_e32 v120, 0xbfb8aa3b, v120
	v_exp_f32_e32 v124, v124
	v_add_f32_e32 v121, v121, v163
	v_mul_f32_e32 v125, 0xbfb8aa3b, v125
	v_mul_f32_e32 v126, 0xbfb8aa3b, v126
	v_exp_f32_e32 v120, v120
	v_mul_f32_e32 v121, 0xbfb8aa3b, v121
	v_exp_f32_e32 v125, v125
	v_exp_f32_e32 v126, v126
	v_exp_f32_e32 v121, v121
	v_add_f32_e32 v124, 1.0, v124
	v_lshlrev_b32_e32 v158, 16, v166
	v_and_b32_e32 v159, 0xffff0000, v166
	v_lshlrev_b32_e32 v160, 16, v167
	v_and_b32_e32 v162, 0xffff0000, v167
	v_lshlrev_b32_e32 v163, 16, v168
	v_and_b32_e32 v166, 0xffff0000, v168
	v_lshlrev_b32_e32 v167, 16, v169
	v_and_b32_e32 v168, 0xffff0000, v169
	v_add_f32_e32 v120, 1.0, v120
	v_add_f32_e32 v125, 1.0, v125
	v_add_f32_e32 v126, 1.0, v126
	v_add_f32_e32 v121, 1.0, v121
	v_add_f32_e32 v122, v122, v164
	v_mul_f32_e32 v122, 0xbfb8aa3b, v122
	v_exp_f32_e32 v122, v122
	v_rcp_f32_e32 v124, v124
	s_nop 0
	v_mul_f32_e32 v124, v124, v158
	v_rcp_f32_e32 v120, v120
	s_nop 0
	v_mul_f32_e32 v163, v120, v163
	v_rcp_f32_e32 v120, v125
	v_rcp_f32_e32 v121, v121
	v_add_f32_e32 v122, 1.0, v122
	v_mul_f32_e32 v120, v120, v159
	v_mul_f32_e32 v125, v121, v166
	v_add_f32_e32 v127, v127, v161
	v_mul_f32_e32 v127, 0xbfb8aa3b, v127
	v_rcp_f32_e32 v121, v126
	v_exp_f32_e32 v127, v127
	v_mul_f32_e32 v121, v121, v160
	v_add_f32_e32 v127, 1.0, v127
	v_add_f32_e32 v123, v123, v165
	v_rcp_f32_e32 v122, v122
	v_mul_f32_e32 v123, 0xbfb8aa3b, v123
	v_mul_f32_e32 v126, v122, v167
	v_exp_f32_e32 v123, v123
	s_nop 0
	v_add_f32_e32 v123, 1.0, v123
	v_rcp_f32_e32 v122, v127
	s_nop 0
	v_mul_f32_e32 v122, v122, v162
	v_rcp_f32_e32 v123, v123
	s_nop 0
	v_mul_f32_e32 v123, v123, v168
	v_cvt_pk_bf16_f32 v120, v124, v120
	v_cvt_pk_bf16_f32 v121, v121, v122
	v_cvt_pk_bf16_f32 v122, v163, v125
	v_cvt_pk_bf16_f32 v123, v126, v123
	v_mov_b32_e32 v124, v170
	v_mov_b32_e32 v125, v171
	v_mov_b32_e32 v126, v172
	v_mov_b32_e32 v127, v173
	v_lshlrev_b64 v[150:151], 11, v[148:149]
	v_lshl_add_u64 v[150:151], s[48:49], 0, v[150:151]
	v_lshl_add_u64 v[150:151], v[150:151], 0, v[146:147]
	global_store_dwordx4 v[150:151], v[120:123], off offset:1024
	s_nop 1
	v_mov_b32_e32 v120, v232
	v_mov_b32_e32 v121, v233
	v_mov_b32_e32 v122, v234
	v_mov_b32_e32 v123, v235
	s_nop 0
	v_mov_b32_e32 v158, v236
	v_mov_b32_e32 v159, v237
	v_mov_b32_e32 v160, v238
	v_mov_b32_e32 v161, v239
	s_nop 0
	v_lshlrev_b32_e32 v149, 16, v124
	v_lshlrev_b32_e32 v163, 16, v126
	v_and_b32_e32 v124, 0xffff0000, v124
	v_and_b32_e32 v126, 0xffff0000, v126
	s_waitcnt lgkmcnt(0)
	v_add_f32_e32 v116, v116, v120
	v_mul_f32_e32 v116, 0xbfb8aa3b, v116
	v_exp_f32_e32 v116, v116
	v_add_f32_e32 v112, v112, v158
	v_mul_f32_e32 v112, 0xbfb8aa3b, v112
	v_exp_f32_e32 v112, v112
	v_add_f32_e32 v116, 1.0, v116
	v_add_f32_e32 v112, 1.0, v112
	v_add_f32_e32 v117, v117, v121
	v_mul_f32_e32 v117, 0xbfb8aa3b, v117
	v_exp_f32_e32 v117, v117
	v_rcp_f32_e32 v116, v116
	s_nop 0
	v_mul_f32_e32 v116, v116, v149
	v_add_f32_e32 v117, 1.0, v117
	v_add_f32_e32 v113, v113, v159
	v_rcp_f32_e32 v112, v112
	v_mul_f32_e32 v113, 0xbfb8aa3b, v113
	v_mul_f32_e32 v120, v112, v163
	v_exp_f32_e32 v113, v113
	s_nop 0
	v_add_f32_e32 v113, 1.0, v113
	v_add_f32_e32 v118, v118, v122
	v_mul_f32_e32 v118, 0xbfb8aa3b, v118
	v_rcp_f32_e32 v112, v117
	v_exp_f32_e32 v118, v118
	v_mul_f32_e32 v112, v112, v124
	v_add_f32_e32 v118, 1.0, v118
	v_add_f32_e32 v114, v114, v160
	v_rcp_f32_e32 v113, v113
	v_mul_f32_e32 v114, 0xbfb8aa3b, v114
	v_mul_f32_e32 v117, v113, v126
	v_exp_f32_e32 v114, v114
	s_nop 0
	v_add_f32_e32 v114, 1.0, v114
	v_add_f32_e32 v119, v119, v123
	v_mul_f32_e32 v119, 0xbfb8aa3b, v119
	v_rcp_f32_e32 v113, v118
	v_exp_f32_e32 v119, v119
	s_nop 0
	v_add_f32_e32 v119, 1.0, v119
	v_add_f32_e32 v115, v115, v161
	v_lshlrev_b32_e32 v164, 16, v127
	v_rcp_f32_e32 v114, v114
	v_mul_f32_e32 v115, 0xbfb8aa3b, v115
	v_mul_f32_e32 v118, v114, v164
	v_exp_f32_e32 v115, v115
	s_nop 0
	v_add_f32_e32 v115, 1.0, v115
	v_rcp_f32_e32 v114, v119
	v_lshlrev_b32_e32 v162, 16, v125
	v_and_b32_e32 v125, 0xffff0000, v125
	v_or_b32_e32 v124, 16, v148
	v_mul_f32_e32 v113, v113, v162
	v_mul_f32_e32 v114, v114, v125
	v_ashrrev_i32_e32 v125, 31, v124
	v_and_b32_e32 v127, 0xffff0000, v127
	v_rcp_f32_e32 v115, v115
	v_cvt_pk_bf16_f32 v112, v116, v112
	v_cvt_pk_bf16_f32 v113, v113, v114
	v_cvt_pk_bf16_f32 v114, v120, v117
	v_lshlrev_b64 v[116:117], 10, v[124:125]
	v_mul_f32_e32 v115, v115, v127
	v_lshl_add_u64 v[116:117], s[60:61], 0, v[116:117]
	v_cvt_pk_bf16_f32 v115, v118, v115
	v_lshl_add_u64 v[126:127], v[116:117], 0, v[146:147]
	global_store_dwordx4 v[150:151], v[112:115], off offset:1280
	s_nop 1
	v_mov_b32_e32 v116, v174
	v_mov_b32_e32 v117, v175
	v_mov_b32_e32 v118, v176
	v_mov_b32_e32 v119, v177
	s_nop 0
	v_mov_b32_e32 v112, v224
	v_mov_b32_e32 v113, v225
	v_mov_b32_e32 v114, v226
	v_mov_b32_e32 v115, v227
	v_mov_b32_e32 v120, v228
	v_mov_b32_e32 v121, v229
	v_mov_b32_e32 v122, v230
	v_mov_b32_e32 v123, v231
	v_lshlrev_b64 v[124:125], 11, v[124:125]
	s_waitcnt lgkmcnt(0)
	v_add_f32_e32 v108, v108, v112
	v_mul_f32_e32 v108, 0xbfb8aa3b, v108
	v_exp_f32_e32 v108, v108
	v_add_f32_e32 v104, v104, v120
	v_mul_f32_e32 v104, 0xbfb8aa3b, v104
	v_exp_f32_e32 v104, v104
	v_add_f32_e32 v108, 1.0, v108
	v_add_f32_e32 v104, 1.0, v104
	v_add_f32_e32 v109, v109, v113
	v_mul_f32_e32 v109, 0xbfb8aa3b, v109
	v_rcp_f32_e32 v108, v108
	v_exp_f32_e32 v109, v109
	v_lshlrev_b32_e32 v149, 16, v116
	v_mul_f32_e32 v108, v108, v149
	v_add_f32_e32 v109, 1.0, v109
	v_add_f32_e32 v105, v105, v121
	v_lshlrev_b32_e32 v150, 16, v118
	v_rcp_f32_e32 v104, v104
	v_mul_f32_e32 v105, 0xbfb8aa3b, v105
	v_mul_f32_e32 v113, v104, v150
	v_exp_f32_e32 v105, v105
	s_nop 0
	v_add_f32_e32 v105, 1.0, v105
	v_add_f32_e32 v110, v110, v114
	v_mul_f32_e32 v110, 0xbfb8aa3b, v110
	v_exp_f32_e32 v110, v110
	v_rcp_f32_e32 v104, v109
	v_and_b32_e32 v116, 0xffff0000, v116
	v_mul_f32_e32 v104, v104, v116
	v_add_f32_e32 v110, 1.0, v110
	v_add_f32_e32 v106, v106, v122
	v_and_b32_e32 v118, 0xffff0000, v118
	v_rcp_f32_e32 v105, v105
	v_mul_f32_e32 v106, 0xbfb8aa3b, v106
	v_mul_f32_e32 v109, v105, v118
	v_exp_f32_e32 v106, v106
	s_nop 0
	v_add_f32_e32 v106, 1.0, v106
	v_add_f32_e32 v111, v111, v115
	v_mul_f32_e32 v111, 0xbfb8aa3b, v111
	v_rcp_f32_e32 v105, v110
	v_exp_f32_e32 v111, v111
	v_lshlrev_b32_e32 v112, 16, v117
	v_mul_f32_e32 v105, v105, v112
	v_add_f32_e32 v111, 1.0, v111
	v_add_f32_e32 v107, v107, v123
	v_lshlrev_b32_e32 v159, 16, v119
	v_rcp_f32_e32 v106, v106
	v_mul_f32_e32 v107, 0xbfb8aa3b, v107
	v_mul_f32_e32 v110, v106, v159
	v_exp_f32_e32 v107, v107
	s_nop 0
	v_add_f32_e32 v107, 1.0, v107
	v_rcp_f32_e32 v106, v111
	v_and_b32_e32 v117, 0xffff0000, v117
	v_mul_f32_e32 v106, v106, v117
	v_and_b32_e32 v119, 0xffff0000, v119
	v_rcp_f32_e32 v107, v107
	v_cvt_pk_bf16_f32 v104, v108, v104
	v_cvt_pk_bf16_f32 v105, v105, v106
	v_cvt_pk_bf16_f32 v106, v113, v109
	v_lshl_add_u64 v[108:109], s[48:49], 0, v[124:125]
	v_mul_f32_e32 v107, v107, v119
	v_lshl_add_u64 v[116:117], v[108:109], 0, v[146:147]
	v_cvt_pk_bf16_f32 v107, v110, v107
	global_store_dwordx4 v[116:117], v[104:107], off offset:1024
	s_nop 1
	v_mov_b32_e32 v108, v178
	v_mov_b32_e32 v109, v179
	v_mov_b32_e32 v110, v180
	v_mov_b32_e32 v111, v181
	s_nop 0
	v_mov_b32_e32 v104, v232
	v_mov_b32_e32 v105, v233
	v_mov_b32_e32 v106, v234
	v_mov_b32_e32 v107, v235
	v_mov_b32_e32 v112, v236
	v_mov_b32_e32 v113, v237
	v_mov_b32_e32 v114, v238
	v_mov_b32_e32 v115, v239
	s_waitcnt lgkmcnt(0)
	v_add_f32_e32 v100, v100, v104
	v_mul_f32_e32 v100, 0xbfb8aa3b, v100
	v_exp_f32_e32 v100, v100
	v_add_f32_e32 v96, v96, v112
	v_mul_f32_e32 v96, 0xbfb8aa3b, v96
	v_exp_f32_e32 v96, v96
	v_add_f32_e32 v100, 1.0, v100
	v_add_f32_e32 v96, 1.0, v96
	v_add_f32_e32 v101, v101, v105
	v_mul_f32_e32 v101, 0xbfb8aa3b, v101
	v_rcp_f32_e32 v100, v100
	v_exp_f32_e32 v101, v101
	v_lshlrev_b32_e32 v118, 16, v108
	v_mul_f32_e32 v100, v100, v118
	v_add_f32_e32 v101, 1.0, v101
	v_add_f32_e32 v97, v97, v113
	v_lshlrev_b32_e32 v119, 16, v110
	v_rcp_f32_e32 v96, v96
	v_mul_f32_e32 v97, 0xbfb8aa3b, v97
	v_mul_f32_e32 v105, v96, v119
	v_exp_f32_e32 v97, v97
	s_nop 0
	v_add_f32_e32 v97, 1.0, v97
	v_add_f32_e32 v102, v102, v106
	v_mul_f32_e32 v102, 0xbfb8aa3b, v102
	v_exp_f32_e32 v102, v102
	v_rcp_f32_e32 v96, v101
	v_and_b32_e32 v108, 0xffff0000, v108
	v_mul_f32_e32 v96, v96, v108
	v_add_f32_e32 v102, 1.0, v102
	v_add_f32_e32 v98, v98, v114
	v_and_b32_e32 v110, 0xffff0000, v110
	v_rcp_f32_e32 v97, v97
	v_mul_f32_e32 v98, 0xbfb8aa3b, v98
	v_mul_f32_e32 v101, v97, v110
	v_exp_f32_e32 v98, v98
	s_nop 0
	v_add_f32_e32 v98, 1.0, v98
	v_add_f32_e32 v103, v103, v107
	v_mul_f32_e32 v103, 0xbfb8aa3b, v103
	v_rcp_f32_e32 v97, v102
	v_exp_f32_e32 v103, v103
	v_lshlrev_b32_e32 v104, 16, v109
	v_mul_f32_e32 v97, v97, v104
	v_add_f32_e32 v103, 1.0, v103
	v_add_f32_e32 v99, v99, v115
	v_lshlrev_b32_e32 v122, 16, v111
	v_rcp_f32_e32 v98, v98
	v_mul_f32_e32 v99, 0xbfb8aa3b, v99
	v_mul_f32_e32 v102, v98, v122
	v_exp_f32_e32 v99, v99
	s_nop 0
	v_add_f32_e32 v99, 1.0, v99
	v_rcp_f32_e32 v98, v103
	v_and_b32_e32 v109, 0xffff0000, v109
	v_or_b32_e32 v108, 32, v148
	v_mul_f32_e32 v98, v98, v109
	v_ashrrev_i32_e32 v109, 31, v108
	v_and_b32_e32 v111, 0xffff0000, v111
	v_rcp_f32_e32 v99, v99
	v_cvt_pk_bf16_f32 v96, v100, v96
	v_cvt_pk_bf16_f32 v97, v97, v98
	v_cvt_pk_bf16_f32 v98, v105, v101
	v_lshlrev_b64 v[100:101], 10, v[108:109]
	v_mul_f32_e32 v99, v99, v111
	v_lshl_add_u64 v[100:101], s[60:61], 0, v[100:101]
	v_cvt_pk_bf16_f32 v99, v102, v99
	v_lshl_add_u64 v[110:111], v[100:101], 0, v[146:147]
	global_store_dwordx4 v[116:117], v[96:99], off offset:1280
	s_nop 1
	v_mov_b32_e32 v100, v182
	v_mov_b32_e32 v101, v183
	v_mov_b32_e32 v102, v184
	v_mov_b32_e32 v103, v185
	s_nop 0
	v_mov_b32_e32 v96, v224
	v_mov_b32_e32 v97, v225
	v_mov_b32_e32 v98, v226
	v_mov_b32_e32 v99, v227
	v_mov_b32_e32 v104, v228
	v_mov_b32_e32 v105, v229
	v_mov_b32_e32 v106, v230
	v_mov_b32_e32 v107, v231
	v_lshlrev_b64 v[108:109], 11, v[108:109]
	s_waitcnt lgkmcnt(0)
	v_add_f32_e32 v92, v92, v96
	v_mul_f32_e32 v92, 0xbfb8aa3b, v92
	v_exp_f32_e32 v92, v92
	v_add_f32_e32 v88, v88, v104
	v_mul_f32_e32 v88, 0xbfb8aa3b, v88
	v_exp_f32_e32 v88, v88
	v_add_f32_e32 v92, 1.0, v92
	v_add_f32_e32 v88, 1.0, v88
	v_add_f32_e32 v93, v93, v97
	v_mul_f32_e32 v93, 0xbfb8aa3b, v93
	v_rcp_f32_e32 v92, v92
	v_exp_f32_e32 v93, v93
	v_lshlrev_b32_e32 v112, 16, v100
	v_mul_f32_e32 v92, v92, v112
	v_add_f32_e32 v93, 1.0, v93
	v_add_f32_e32 v89, v89, v105
	v_lshlrev_b32_e32 v113, 16, v102
	v_rcp_f32_e32 v88, v88
	v_mul_f32_e32 v89, 0xbfb8aa3b, v89
	v_mul_f32_e32 v97, v88, v113
	v_exp_f32_e32 v89, v89
	s_nop 0
	v_add_f32_e32 v89, 1.0, v89
	v_add_f32_e32 v94, v94, v98
	v_mul_f32_e32 v94, 0xbfb8aa3b, v94
	v_exp_f32_e32 v94, v94
	v_rcp_f32_e32 v88, v93
	v_and_b32_e32 v100, 0xffff0000, v100
	v_mul_f32_e32 v88, v88, v100
	v_add_f32_e32 v94, 1.0, v94
	v_add_f32_e32 v90, v90, v106
	v_and_b32_e32 v102, 0xffff0000, v102
	v_rcp_f32_e32 v89, v89
	v_mul_f32_e32 v90, 0xbfb8aa3b, v90
	v_mul_f32_e32 v93, v89, v102
	v_exp_f32_e32 v90, v90
	s_nop 0
	v_add_f32_e32 v90, 1.0, v90
	v_add_f32_e32 v95, v95, v99
	v_mul_f32_e32 v95, 0xbfb8aa3b, v95
	v_rcp_f32_e32 v89, v94
	v_exp_f32_e32 v95, v95
	v_lshlrev_b32_e32 v96, 16, v101
	v_mul_f32_e32 v89, v89, v96
	v_add_f32_e32 v95, 1.0, v95
	v_add_f32_e32 v91, v91, v107
	v_lshlrev_b32_e32 v116, 16, v103
	v_rcp_f32_e32 v90, v90
	v_mul_f32_e32 v91, 0xbfb8aa3b, v91
	v_mul_f32_e32 v94, v90, v116
	v_exp_f32_e32 v91, v91
	s_nop 0
	v_add_f32_e32 v91, 1.0, v91
	v_rcp_f32_e32 v90, v95
	v_and_b32_e32 v101, 0xffff0000, v101
	v_mul_f32_e32 v90, v90, v101
	v_and_b32_e32 v103, 0xffff0000, v103
	v_rcp_f32_e32 v91, v91
	v_cvt_pk_bf16_f32 v88, v92, v88
	v_cvt_pk_bf16_f32 v89, v89, v90
	v_cvt_pk_bf16_f32 v90, v97, v93
	v_lshl_add_u64 v[92:93], s[48:49], 0, v[108:109]
	v_mul_f32_e32 v91, v91, v103
	v_lshl_add_u64 v[100:101], v[92:93], 0, v[146:147]
	v_cvt_pk_bf16_f32 v91, v94, v91
	global_store_dwordx4 v[100:101], v[88:91], off offset:1024
	s_nop 1
	v_mov_b32_e32 v92, v186
	v_mov_b32_e32 v93, v187
	v_mov_b32_e32 v94, v188
	v_mov_b32_e32 v95, v189
	s_nop 0
	v_mov_b32_e32 v88, v232
	v_mov_b32_e32 v89, v233
	v_mov_b32_e32 v90, v234
	v_mov_b32_e32 v91, v235
	v_mov_b32_e32 v96, v236
	v_mov_b32_e32 v97, v237
	v_mov_b32_e32 v98, v238
	v_mov_b32_e32 v99, v239
	s_waitcnt lgkmcnt(0)
	v_add_f32_e32 v84, v84, v88
	v_mul_f32_e32 v84, 0xbfb8aa3b, v84
	v_exp_f32_e32 v84, v84
	v_add_f32_e32 v80, v80, v96
	v_mul_f32_e32 v80, 0xbfb8aa3b, v80
	v_exp_f32_e32 v80, v80
	v_add_f32_e32 v84, 1.0, v84
	v_add_f32_e32 v80, 1.0, v80
	v_add_f32_e32 v85, v85, v89
	v_mul_f32_e32 v85, 0xbfb8aa3b, v85
	v_rcp_f32_e32 v84, v84
	v_exp_f32_e32 v85, v85
	v_lshlrev_b32_e32 v102, 16, v92
	v_mul_f32_e32 v84, v84, v102
	v_add_f32_e32 v85, 1.0, v85
	v_add_f32_e32 v81, v81, v97
	v_lshlrev_b32_e32 v103, 16, v94
	v_rcp_f32_e32 v80, v80
	v_mul_f32_e32 v81, 0xbfb8aa3b, v81
	v_mul_f32_e32 v89, v80, v103
	v_exp_f32_e32 v81, v81
	s_nop 0
	v_add_f32_e32 v81, 1.0, v81
	v_add_f32_e32 v86, v86, v90
	v_mul_f32_e32 v86, 0xbfb8aa3b, v86
	v_exp_f32_e32 v86, v86
	v_rcp_f32_e32 v80, v85
	v_and_b32_e32 v92, 0xffff0000, v92
	v_mul_f32_e32 v80, v80, v92
	v_add_f32_e32 v86, 1.0, v86
	v_add_f32_e32 v82, v82, v98
	v_and_b32_e32 v94, 0xffff0000, v94
	v_rcp_f32_e32 v81, v81
	v_mul_f32_e32 v82, 0xbfb8aa3b, v82
	v_mul_f32_e32 v85, v81, v94
	v_exp_f32_e32 v82, v82
	s_nop 0
	v_add_f32_e32 v82, 1.0, v82
	v_add_f32_e32 v87, v87, v91
	v_mul_f32_e32 v87, 0xbfb8aa3b, v87
	v_rcp_f32_e32 v81, v86
	v_exp_f32_e32 v87, v87
	v_lshlrev_b32_e32 v88, 16, v93
	v_mul_f32_e32 v81, v81, v88
	v_add_f32_e32 v87, 1.0, v87
	v_add_f32_e32 v83, v83, v99
	v_lshlrev_b32_e32 v106, 16, v95
	v_rcp_f32_e32 v82, v82
	v_mul_f32_e32 v83, 0xbfb8aa3b, v83
	v_mul_f32_e32 v86, v82, v106
	v_exp_f32_e32 v83, v83
	s_nop 0
	v_add_f32_e32 v83, 1.0, v83
	v_rcp_f32_e32 v82, v87
	v_and_b32_e32 v93, 0xffff0000, v93
	v_or_b32_e32 v92, 48, v148
	v_mul_f32_e32 v82, v82, v93
	v_ashrrev_i32_e32 v93, 31, v92
	v_and_b32_e32 v95, 0xffff0000, v95
	v_rcp_f32_e32 v83, v83
	v_cvt_pk_bf16_f32 v80, v84, v80
	v_cvt_pk_bf16_f32 v81, v81, v82
	v_cvt_pk_bf16_f32 v82, v89, v85
	v_lshlrev_b64 v[84:85], 10, v[92:93]
	v_mul_f32_e32 v83, v83, v95
	v_lshl_add_u64 v[84:85], s[60:61], 0, v[84:85]
	v_cvt_pk_bf16_f32 v83, v86, v83
	v_lshl_add_u64 v[94:95], v[84:85], 0, v[146:147]
	global_store_dwordx4 v[100:101], v[80:83], off offset:1280
	s_nop 1
	v_mov_b32_e32 v84, v190
	v_mov_b32_e32 v85, v191
	v_mov_b32_e32 v86, v192
	v_mov_b32_e32 v87, v193
	s_nop 0
	v_mov_b32_e32 v80, v224
	v_mov_b32_e32 v81, v225
	v_mov_b32_e32 v82, v226
	v_mov_b32_e32 v83, v227
	v_mov_b32_e32 v88, v228
	v_mov_b32_e32 v89, v229
	v_mov_b32_e32 v90, v230
	v_mov_b32_e32 v91, v231
	v_lshlrev_b64 v[92:93], 11, v[92:93]
	s_waitcnt lgkmcnt(0)
	v_add_f32_e32 v76, v76, v80
	v_mul_f32_e32 v76, 0xbfb8aa3b, v76
	v_exp_f32_e32 v76, v76
	v_add_f32_e32 v72, v72, v88
	v_mul_f32_e32 v72, 0xbfb8aa3b, v72
	v_exp_f32_e32 v72, v72
	v_add_f32_e32 v76, 1.0, v76
	v_add_f32_e32 v72, 1.0, v72
	v_add_f32_e32 v77, v77, v81
	v_mul_f32_e32 v77, 0xbfb8aa3b, v77
	v_rcp_f32_e32 v76, v76
	v_exp_f32_e32 v77, v77
	v_lshlrev_b32_e32 v96, 16, v84
	v_mul_f32_e32 v76, v76, v96
	v_add_f32_e32 v77, 1.0, v77
	v_add_f32_e32 v73, v73, v89
	v_lshlrev_b32_e32 v97, 16, v86
	v_rcp_f32_e32 v72, v72
	v_mul_f32_e32 v73, 0xbfb8aa3b, v73
	v_mul_f32_e32 v81, v72, v97
	v_exp_f32_e32 v73, v73
	s_nop 0
	v_add_f32_e32 v73, 1.0, v73
	v_add_f32_e32 v78, v78, v82
	v_mul_f32_e32 v78, 0xbfb8aa3b, v78
	v_exp_f32_e32 v78, v78
	v_rcp_f32_e32 v72, v77
	v_and_b32_e32 v84, 0xffff0000, v84
	v_mul_f32_e32 v72, v72, v84
	v_add_f32_e32 v78, 1.0, v78
	v_add_f32_e32 v74, v74, v90
	v_and_b32_e32 v86, 0xffff0000, v86
	v_rcp_f32_e32 v73, v73
	v_mul_f32_e32 v74, 0xbfb8aa3b, v74
	v_mul_f32_e32 v77, v73, v86
	v_exp_f32_e32 v74, v74
	s_nop 0
	v_add_f32_e32 v74, 1.0, v74
	v_add_f32_e32 v79, v79, v83
	v_mul_f32_e32 v79, 0xbfb8aa3b, v79
	v_rcp_f32_e32 v73, v78
	v_exp_f32_e32 v79, v79
	v_lshlrev_b32_e32 v80, 16, v85
	v_mul_f32_e32 v73, v73, v80
	v_add_f32_e32 v79, 1.0, v79
	v_add_f32_e32 v75, v75, v91
	v_lshlrev_b32_e32 v100, 16, v87
	v_rcp_f32_e32 v74, v74
	v_mul_f32_e32 v75, 0xbfb8aa3b, v75
	v_mul_f32_e32 v78, v74, v100
	v_exp_f32_e32 v75, v75
	s_nop 0
	v_add_f32_e32 v75, 1.0, v75
	v_rcp_f32_e32 v74, v79
	v_and_b32_e32 v85, 0xffff0000, v85
	v_mul_f32_e32 v74, v74, v85
	v_and_b32_e32 v87, 0xffff0000, v87
	v_rcp_f32_e32 v75, v75
	v_cvt_pk_bf16_f32 v72, v76, v72
	v_cvt_pk_bf16_f32 v73, v73, v74
	v_cvt_pk_bf16_f32 v74, v81, v77
	v_lshl_add_u64 v[76:77], s[48:49], 0, v[92:93]
	v_mul_f32_e32 v75, v75, v87
	v_lshl_add_u64 v[84:85], v[76:77], 0, v[146:147]
	v_cvt_pk_bf16_f32 v75, v78, v75
	global_store_dwordx4 v[84:85], v[72:75], off offset:1024
	s_nop 1
	v_mov_b32_e32 v76, v194
	v_mov_b32_e32 v77, v195
	v_mov_b32_e32 v78, v196
	v_mov_b32_e32 v79, v197
	s_nop 0
	v_mov_b32_e32 v72, v232
	v_mov_b32_e32 v73, v233
	v_mov_b32_e32 v74, v234
	v_mov_b32_e32 v75, v235
	v_mov_b32_e32 v80, v236
	v_mov_b32_e32 v81, v237
	v_mov_b32_e32 v82, v238
	v_mov_b32_e32 v83, v239
	s_waitcnt lgkmcnt(0)
	v_add_f32_e32 v68, v68, v72
	v_mul_f32_e32 v68, 0xbfb8aa3b, v68
	v_exp_f32_e32 v68, v68
	v_add_f32_e32 v64, v64, v80
	v_mul_f32_e32 v64, 0xbfb8aa3b, v64
	v_exp_f32_e32 v64, v64
	v_add_f32_e32 v68, 1.0, v68
	v_add_f32_e32 v64, 1.0, v64
	v_add_f32_e32 v69, v69, v73
	v_mul_f32_e32 v69, 0xbfb8aa3b, v69
	v_rcp_f32_e32 v68, v68
	v_exp_f32_e32 v69, v69
	v_lshlrev_b32_e32 v86, 16, v76
	v_mul_f32_e32 v68, v68, v86
	v_add_f32_e32 v69, 1.0, v69
	v_add_f32_e32 v65, v65, v81
	v_lshlrev_b32_e32 v87, 16, v78
	v_rcp_f32_e32 v64, v64
	v_mul_f32_e32 v65, 0xbfb8aa3b, v65
	v_mul_f32_e32 v73, v64, v87
	v_exp_f32_e32 v65, v65
	s_nop 0
	v_add_f32_e32 v65, 1.0, v65
	v_add_f32_e32 v70, v70, v74
	v_mul_f32_e32 v70, 0xbfb8aa3b, v70
	v_exp_f32_e32 v70, v70
	v_rcp_f32_e32 v64, v69
	v_and_b32_e32 v76, 0xffff0000, v76
	v_mul_f32_e32 v64, v64, v76
	v_add_f32_e32 v70, 1.0, v70
	v_add_f32_e32 v66, v66, v82
	v_and_b32_e32 v78, 0xffff0000, v78
	v_rcp_f32_e32 v65, v65
	v_mul_f32_e32 v66, 0xbfb8aa3b, v66
	v_mul_f32_e32 v69, v65, v78
	v_exp_f32_e32 v66, v66
	s_nop 0
	v_add_f32_e32 v66, 1.0, v66
	v_add_f32_e32 v71, v71, v75
	v_mul_f32_e32 v71, 0xbfb8aa3b, v71
	v_rcp_f32_e32 v65, v70
	v_exp_f32_e32 v71, v71
	v_lshlrev_b32_e32 v72, 16, v77
	v_mul_f32_e32 v65, v65, v72
	v_add_f32_e32 v71, 1.0, v71
	v_add_f32_e32 v67, v67, v83
	v_lshlrev_b32_e32 v90, 16, v79
	v_rcp_f32_e32 v66, v66
	v_mul_f32_e32 v67, 0xbfb8aa3b, v67
	v_mul_f32_e32 v70, v66, v90
	v_exp_f32_e32 v67, v67
	s_nop 0
	v_add_f32_e32 v67, 1.0, v67
	v_rcp_f32_e32 v66, v71
	v_and_b32_e32 v77, 0xffff0000, v77
	v_add_u32_e32 v76, 0x80, v148
	v_mul_f32_e32 v66, v66, v77
	v_ashrrev_i32_e32 v77, 31, v76
	v_and_b32_e32 v79, 0xffff0000, v79
	v_rcp_f32_e32 v67, v67
	v_cvt_pk_bf16_f32 v64, v68, v64
	v_cvt_pk_bf16_f32 v65, v65, v66
	v_cvt_pk_bf16_f32 v66, v73, v69
	v_lshlrev_b64 v[68:69], 10, v[76:77]
	v_mul_f32_e32 v67, v67, v79
	v_lshl_add_u64 v[68:69], s[60:61], 0, v[68:69]
	v_cvt_pk_bf16_f32 v67, v70, v67
	v_lshl_add_u64 v[78:79], v[68:69], 0, v[146:147]
	global_store_dwordx4 v[84:85], v[64:67], off offset:1280
	s_nop 1
	v_mov_b32_e32 v68, v198
	v_mov_b32_e32 v69, v199
	v_mov_b32_e32 v70, v200
	v_mov_b32_e32 v71, v201
	s_nop 0
	v_mov_b32_e32 v64, v224
	v_mov_b32_e32 v65, v225
	v_mov_b32_e32 v66, v226
	v_mov_b32_e32 v67, v227
	v_mov_b32_e32 v72, v228
	v_mov_b32_e32 v73, v229
	v_mov_b32_e32 v74, v230
	v_mov_b32_e32 v75, v231
	v_lshlrev_b64 v[76:77], 11, v[76:77]
	s_waitcnt lgkmcnt(0)
	v_add_f32_e32 v60, v60, v64
	v_mul_f32_e32 v60, 0xbfb8aa3b, v60
	v_exp_f32_e32 v60, v60
	v_add_f32_e32 v56, v56, v72
	v_mul_f32_e32 v56, 0xbfb8aa3b, v56
	v_exp_f32_e32 v56, v56
	v_add_f32_e32 v60, 1.0, v60
	v_add_f32_e32 v56, 1.0, v56
	v_add_f32_e32 v61, v61, v65
	v_mul_f32_e32 v61, 0xbfb8aa3b, v61
	v_rcp_f32_e32 v60, v60
	v_exp_f32_e32 v61, v61
	v_lshlrev_b32_e32 v80, 16, v68
	v_mul_f32_e32 v60, v60, v80
	v_add_f32_e32 v61, 1.0, v61
	v_add_f32_e32 v57, v57, v73
	v_lshlrev_b32_e32 v81, 16, v70
	v_rcp_f32_e32 v56, v56
	v_mul_f32_e32 v57, 0xbfb8aa3b, v57
	v_mul_f32_e32 v65, v56, v81
	v_exp_f32_e32 v57, v57
	s_nop 0
	v_add_f32_e32 v57, 1.0, v57
	v_add_f32_e32 v62, v62, v66
	v_mul_f32_e32 v62, 0xbfb8aa3b, v62
	v_exp_f32_e32 v62, v62
	v_rcp_f32_e32 v56, v61
	v_and_b32_e32 v68, 0xffff0000, v68
	v_mul_f32_e32 v56, v56, v68
	v_add_f32_e32 v62, 1.0, v62
	v_add_f32_e32 v58, v58, v74
	v_and_b32_e32 v70, 0xffff0000, v70
	v_rcp_f32_e32 v57, v57
	v_mul_f32_e32 v58, 0xbfb8aa3b, v58
	v_mul_f32_e32 v61, v57, v70
	v_exp_f32_e32 v58, v58
	s_nop 0
	v_add_f32_e32 v58, 1.0, v58
	v_add_f32_e32 v63, v63, v67
	v_mul_f32_e32 v63, 0xbfb8aa3b, v63
	v_rcp_f32_e32 v57, v62
	v_exp_f32_e32 v63, v63
	v_lshlrev_b32_e32 v64, 16, v69
	v_mul_f32_e32 v57, v57, v64
	v_add_f32_e32 v63, 1.0, v63
	v_add_f32_e32 v59, v59, v75
	v_lshlrev_b32_e32 v84, 16, v71
	v_rcp_f32_e32 v58, v58
	v_mul_f32_e32 v59, 0xbfb8aa3b, v59
	v_mul_f32_e32 v62, v58, v84
	v_exp_f32_e32 v59, v59
	s_nop 0
	v_add_f32_e32 v59, 1.0, v59
	v_rcp_f32_e32 v58, v63
	v_and_b32_e32 v69, 0xffff0000, v69
	v_mul_f32_e32 v58, v58, v69
	v_and_b32_e32 v71, 0xffff0000, v71
	v_rcp_f32_e32 v59, v59
	v_cvt_pk_bf16_f32 v56, v60, v56
	v_cvt_pk_bf16_f32 v57, v57, v58
	v_cvt_pk_bf16_f32 v58, v65, v61
	v_lshl_add_u64 v[60:61], s[48:49], 0, v[76:77]
	v_mul_f32_e32 v59, v59, v71
	v_lshl_add_u64 v[68:69], v[60:61], 0, v[146:147]
	v_cvt_pk_bf16_f32 v59, v62, v59
	global_store_dwordx4 v[68:69], v[56:59], off offset:1024
	s_nop 1
	v_mov_b32_e32 v60, v202
	v_mov_b32_e32 v61, v203
	v_mov_b32_e32 v62, v204
	v_mov_b32_e32 v63, v205
	s_nop 0
	v_mov_b32_e32 v56, v232
	v_mov_b32_e32 v57, v233
	v_mov_b32_e32 v58, v234
	v_mov_b32_e32 v59, v235
	v_mov_b32_e32 v64, v236
	v_mov_b32_e32 v65, v237
	v_mov_b32_e32 v66, v238
	v_mov_b32_e32 v67, v239
	s_waitcnt lgkmcnt(0)
	v_add_f32_e32 v52, v52, v56
	v_mul_f32_e32 v52, 0xbfb8aa3b, v52
	v_exp_f32_e32 v52, v52
	v_add_f32_e32 v48, v48, v64
	v_mul_f32_e32 v48, 0xbfb8aa3b, v48
	v_exp_f32_e32 v48, v48
	v_add_f32_e32 v52, 1.0, v52
	v_add_f32_e32 v48, 1.0, v48
	v_add_f32_e32 v53, v53, v57
	v_mul_f32_e32 v53, 0xbfb8aa3b, v53
	v_rcp_f32_e32 v52, v52
	v_exp_f32_e32 v53, v53
	v_lshlrev_b32_e32 v70, 16, v60
	v_mul_f32_e32 v52, v52, v70
	v_add_f32_e32 v53, 1.0, v53
	v_add_f32_e32 v49, v49, v65
	v_lshlrev_b32_e32 v71, 16, v62
	v_rcp_f32_e32 v48, v48
	v_mul_f32_e32 v49, 0xbfb8aa3b, v49
	v_mul_f32_e32 v57, v48, v71
	v_exp_f32_e32 v49, v49
	s_nop 0
	v_add_f32_e32 v49, 1.0, v49
	v_add_f32_e32 v54, v54, v58
	v_mul_f32_e32 v54, 0xbfb8aa3b, v54
	v_exp_f32_e32 v54, v54
	v_rcp_f32_e32 v48, v53
	v_and_b32_e32 v60, 0xffff0000, v60
	v_mul_f32_e32 v48, v48, v60
	v_add_f32_e32 v54, 1.0, v54
	v_add_f32_e32 v50, v50, v66
	v_and_b32_e32 v62, 0xffff0000, v62
	v_rcp_f32_e32 v49, v49
	v_mul_f32_e32 v50, 0xbfb8aa3b, v50
	v_mul_f32_e32 v53, v49, v62
	v_exp_f32_e32 v50, v50
	s_nop 0
	v_add_f32_e32 v50, 1.0, v50
	v_add_f32_e32 v55, v55, v59
	v_mul_f32_e32 v55, 0xbfb8aa3b, v55
	v_rcp_f32_e32 v49, v54
	v_exp_f32_e32 v55, v55
	v_lshlrev_b32_e32 v56, 16, v61
	v_mul_f32_e32 v49, v49, v56
	v_add_f32_e32 v55, 1.0, v55
	v_add_f32_e32 v51, v51, v67
	v_lshlrev_b32_e32 v74, 16, v63
	v_rcp_f32_e32 v50, v50
	v_mul_f32_e32 v51, 0xbfb8aa3b, v51
	v_mul_f32_e32 v54, v50, v74
	v_exp_f32_e32 v51, v51
	s_nop 0
	v_add_f32_e32 v51, 1.0, v51
	v_rcp_f32_e32 v50, v55
	v_and_b32_e32 v61, 0xffff0000, v61
	v_add_u32_e32 v60, 0x90, v148
	v_mul_f32_e32 v50, v50, v61
	v_ashrrev_i32_e32 v61, 31, v60
	v_and_b32_e32 v63, 0xffff0000, v63
	v_rcp_f32_e32 v51, v51
	v_cvt_pk_bf16_f32 v48, v52, v48
	v_cvt_pk_bf16_f32 v49, v49, v50
	v_cvt_pk_bf16_f32 v50, v57, v53
	v_lshlrev_b64 v[52:53], 10, v[60:61]
	v_mul_f32_e32 v51, v51, v63
	v_lshl_add_u64 v[52:53], s[60:61], 0, v[52:53]
	v_cvt_pk_bf16_f32 v51, v54, v51
	v_lshl_add_u64 v[62:63], v[52:53], 0, v[146:147]
	global_store_dwordx4 v[68:69], v[48:51], off offset:1280
	s_nop 1
	v_mov_b32_e32 v52, v206
	v_mov_b32_e32 v53, v207
	v_mov_b32_e32 v54, v208
	v_mov_b32_e32 v55, v209
	s_nop 0
	v_mov_b32_e32 v48, v224
	v_mov_b32_e32 v49, v225
	v_mov_b32_e32 v50, v226
	v_mov_b32_e32 v51, v227
	v_mov_b32_e32 v56, v228
	v_mov_b32_e32 v57, v229
	v_mov_b32_e32 v58, v230
	v_mov_b32_e32 v59, v231
	v_lshlrev_b64 v[60:61], 11, v[60:61]
	s_waitcnt lgkmcnt(0)
	v_add_f32_e32 v44, v44, v48
	v_mul_f32_e32 v44, 0xbfb8aa3b, v44
	v_exp_f32_e32 v44, v44
	v_add_f32_e32 v40, v40, v56
	v_mul_f32_e32 v40, 0xbfb8aa3b, v40
	v_exp_f32_e32 v40, v40
	v_add_f32_e32 v44, 1.0, v44
	v_add_f32_e32 v40, 1.0, v40
	v_add_f32_e32 v45, v45, v49
	v_mul_f32_e32 v45, 0xbfb8aa3b, v45
	v_rcp_f32_e32 v44, v44
	v_exp_f32_e32 v45, v45
	v_lshlrev_b32_e32 v64, 16, v52
	v_mul_f32_e32 v44, v44, v64
	v_add_f32_e32 v45, 1.0, v45
	v_add_f32_e32 v41, v41, v57
	v_lshlrev_b32_e32 v65, 16, v54
	v_rcp_f32_e32 v40, v40
	v_mul_f32_e32 v41, 0xbfb8aa3b, v41
	v_mul_f32_e32 v49, v40, v65
	v_exp_f32_e32 v41, v41
	s_nop 0
	v_add_f32_e32 v41, 1.0, v41
	v_add_f32_e32 v46, v46, v50
	v_mul_f32_e32 v46, 0xbfb8aa3b, v46
	v_exp_f32_e32 v46, v46
	v_rcp_f32_e32 v40, v45
	v_and_b32_e32 v52, 0xffff0000, v52
	v_mul_f32_e32 v40, v40, v52
	v_add_f32_e32 v46, 1.0, v46
	v_add_f32_e32 v42, v42, v58
	v_and_b32_e32 v54, 0xffff0000, v54
	v_rcp_f32_e32 v41, v41
	v_mul_f32_e32 v42, 0xbfb8aa3b, v42
	v_mul_f32_e32 v45, v41, v54
	v_exp_f32_e32 v42, v42
	s_nop 0
	v_add_f32_e32 v42, 1.0, v42
	v_add_f32_e32 v47, v47, v51
	v_mul_f32_e32 v47, 0xbfb8aa3b, v47
	v_rcp_f32_e32 v41, v46
	v_exp_f32_e32 v47, v47
	v_lshlrev_b32_e32 v48, 16, v53
	v_mul_f32_e32 v41, v41, v48
	v_add_f32_e32 v47, 1.0, v47
	v_add_f32_e32 v43, v43, v59
	v_lshlrev_b32_e32 v68, 16, v55
	v_rcp_f32_e32 v42, v42
	v_mul_f32_e32 v43, 0xbfb8aa3b, v43
	v_mul_f32_e32 v46, v42, v68
	v_exp_f32_e32 v43, v43
	s_nop 0
	v_add_f32_e32 v43, 1.0, v43
	v_rcp_f32_e32 v42, v47
	v_and_b32_e32 v53, 0xffff0000, v53
	v_mul_f32_e32 v42, v42, v53
	v_and_b32_e32 v55, 0xffff0000, v55
	v_rcp_f32_e32 v43, v43
	v_cvt_pk_bf16_f32 v40, v44, v40
	v_cvt_pk_bf16_f32 v41, v41, v42
	v_cvt_pk_bf16_f32 v42, v49, v45
	v_lshl_add_u64 v[44:45], s[48:49], 0, v[60:61]
	v_mul_f32_e32 v43, v43, v55
	v_lshl_add_u64 v[52:53], v[44:45], 0, v[146:147]
	v_cvt_pk_bf16_f32 v43, v46, v43
	global_store_dwordx4 v[52:53], v[40:43], off offset:1024
	s_nop 1
	v_mov_b32_e32 v44, v210
	v_mov_b32_e32 v45, v211
	v_mov_b32_e32 v46, v212
	v_mov_b32_e32 v47, v213
	s_nop 0
	v_mov_b32_e32 v40, v232
	v_mov_b32_e32 v41, v233
	v_mov_b32_e32 v42, v234
	v_mov_b32_e32 v43, v235
	v_mov_b32_e32 v48, v236
	v_mov_b32_e32 v49, v237
	v_mov_b32_e32 v50, v238
	v_mov_b32_e32 v51, v239
	s_waitcnt lgkmcnt(0)
	v_add_f32_e32 v36, v36, v40
	v_mul_f32_e32 v36, 0xbfb8aa3b, v36
	v_exp_f32_e32 v36, v36
	v_add_f32_e32 v32, v32, v48
	v_mul_f32_e32 v32, 0xbfb8aa3b, v32
	v_exp_f32_e32 v32, v32
	v_add_f32_e32 v36, 1.0, v36
	v_add_f32_e32 v32, 1.0, v32
	v_add_f32_e32 v37, v37, v41
	v_mul_f32_e32 v37, 0xbfb8aa3b, v37
	v_rcp_f32_e32 v36, v36
	v_exp_f32_e32 v37, v37
	v_lshlrev_b32_e32 v54, 16, v44
	v_mul_f32_e32 v36, v36, v54
	v_add_f32_e32 v37, 1.0, v37
	v_add_f32_e32 v33, v33, v49
	v_lshlrev_b32_e32 v55, 16, v46
	v_rcp_f32_e32 v32, v32
	v_mul_f32_e32 v33, 0xbfb8aa3b, v33
	v_mul_f32_e32 v41, v32, v55
	v_exp_f32_e32 v33, v33
	s_nop 0
	v_add_f32_e32 v33, 1.0, v33
	v_add_f32_e32 v38, v38, v42
	v_mul_f32_e32 v38, 0xbfb8aa3b, v38
	v_exp_f32_e32 v38, v38
	v_rcp_f32_e32 v32, v37
	v_and_b32_e32 v44, 0xffff0000, v44
	v_mul_f32_e32 v32, v32, v44
	v_add_f32_e32 v38, 1.0, v38
	v_add_f32_e32 v34, v34, v50
	v_and_b32_e32 v46, 0xffff0000, v46
	v_rcp_f32_e32 v33, v33
	v_mul_f32_e32 v34, 0xbfb8aa3b, v34
	v_mul_f32_e32 v37, v33, v46
	v_exp_f32_e32 v34, v34
	s_nop 0
	v_add_f32_e32 v34, 1.0, v34
	v_add_f32_e32 v39, v39, v43
	v_mul_f32_e32 v39, 0xbfb8aa3b, v39
	v_rcp_f32_e32 v33, v38
	v_exp_f32_e32 v39, v39
	v_lshlrev_b32_e32 v40, 16, v45
	v_mul_f32_e32 v33, v33, v40
	v_add_f32_e32 v39, 1.0, v39
	v_add_f32_e32 v35, v35, v51
	v_lshlrev_b32_e32 v58, 16, v47
	v_rcp_f32_e32 v34, v34
	v_mul_f32_e32 v35, 0xbfb8aa3b, v35
	v_mul_f32_e32 v38, v34, v58
	v_exp_f32_e32 v35, v35
	s_nop 0
	v_add_f32_e32 v35, 1.0, v35
	v_rcp_f32_e32 v34, v39
	v_and_b32_e32 v45, 0xffff0000, v45
	v_add_u32_e32 v44, 0xa0, v148
	v_mul_f32_e32 v34, v34, v45
	v_ashrrev_i32_e32 v45, 31, v44
	v_and_b32_e32 v47, 0xffff0000, v47
	v_rcp_f32_e32 v35, v35
	v_cvt_pk_bf16_f32 v32, v36, v32
	v_cvt_pk_bf16_f32 v33, v33, v34
	v_cvt_pk_bf16_f32 v34, v41, v37
	v_lshlrev_b64 v[36:37], 10, v[44:45]
	v_mul_f32_e32 v35, v35, v47
	v_lshl_add_u64 v[36:37], s[60:61], 0, v[36:37]
	v_cvt_pk_bf16_f32 v35, v38, v35
	v_lshl_add_u64 v[46:47], v[36:37], 0, v[146:147]
	global_store_dwordx4 v[52:53], v[32:35], off offset:1280
	s_nop 1
	v_mov_b32_e32 v36, v240
	v_mov_b32_e32 v37, v241
	v_mov_b32_e32 v38, v242
	v_mov_b32_e32 v39, v243
	s_nop 0
	v_mov_b32_e32 v32, v224
	v_mov_b32_e32 v33, v225
	v_mov_b32_e32 v34, v226
	v_mov_b32_e32 v35, v227
	v_mov_b32_e32 v40, v228
	v_mov_b32_e32 v41, v229
	v_mov_b32_e32 v42, v230
	v_mov_b32_e32 v43, v231
	v_lshlrev_b64 v[44:45], 11, v[44:45]
	s_waitcnt lgkmcnt(0)
	v_add_f32_e32 v28, v28, v32
	v_mul_f32_e32 v28, 0xbfb8aa3b, v28
	v_exp_f32_e32 v28, v28
	v_add_f32_e32 v24, v24, v40
	v_mul_f32_e32 v24, 0xbfb8aa3b, v24
	v_exp_f32_e32 v24, v24
	v_add_f32_e32 v28, 1.0, v28
	v_add_f32_e32 v24, 1.0, v24
	v_add_f32_e32 v29, v29, v33
	v_mul_f32_e32 v29, 0xbfb8aa3b, v29
	v_rcp_f32_e32 v28, v28
	v_exp_f32_e32 v29, v29
	v_lshlrev_b32_e32 v48, 16, v36
	v_mul_f32_e32 v28, v28, v48
	v_add_f32_e32 v29, 1.0, v29
	v_add_f32_e32 v25, v25, v41
	v_lshlrev_b32_e32 v49, 16, v38
	v_rcp_f32_e32 v24, v24
	v_mul_f32_e32 v25, 0xbfb8aa3b, v25
	v_mul_f32_e32 v33, v24, v49
	v_exp_f32_e32 v25, v25
	s_nop 0
	v_add_f32_e32 v25, 1.0, v25
	v_add_f32_e32 v30, v30, v34
	v_mul_f32_e32 v30, 0xbfb8aa3b, v30
	v_exp_f32_e32 v30, v30
	v_rcp_f32_e32 v24, v29
	v_and_b32_e32 v36, 0xffff0000, v36
	v_mul_f32_e32 v24, v24, v36
	v_add_f32_e32 v30, 1.0, v30
	v_add_f32_e32 v26, v26, v42
	v_and_b32_e32 v38, 0xffff0000, v38
	v_rcp_f32_e32 v25, v25
	v_mul_f32_e32 v26, 0xbfb8aa3b, v26
	v_mul_f32_e32 v29, v25, v38
	v_exp_f32_e32 v26, v26
	s_nop 0
	v_add_f32_e32 v26, 1.0, v26
	v_add_f32_e32 v31, v31, v35
	v_mul_f32_e32 v31, 0xbfb8aa3b, v31
	v_rcp_f32_e32 v25, v30
	v_exp_f32_e32 v31, v31
	v_lshlrev_b32_e32 v32, 16, v37
	v_mul_f32_e32 v25, v25, v32
	v_add_f32_e32 v31, 1.0, v31
	v_add_f32_e32 v27, v27, v43
	v_lshlrev_b32_e32 v52, 16, v39
	v_rcp_f32_e32 v26, v26
	v_mul_f32_e32 v27, 0xbfb8aa3b, v27
	v_mul_f32_e32 v30, v26, v52
	v_exp_f32_e32 v27, v27
	s_nop 0
	v_add_f32_e32 v27, 1.0, v27
	v_rcp_f32_e32 v26, v31
	v_and_b32_e32 v37, 0xffff0000, v37
	v_mul_f32_e32 v26, v26, v37
	v_and_b32_e32 v39, 0xffff0000, v39
	v_rcp_f32_e32 v27, v27
	v_cvt_pk_bf16_f32 v24, v28, v24
	v_cvt_pk_bf16_f32 v25, v25, v26
	v_cvt_pk_bf16_f32 v26, v33, v29
	v_lshl_add_u64 v[28:29], s[48:49], 0, v[44:45]
	v_mul_f32_e32 v27, v27, v39
	v_lshl_add_u64 v[36:37], v[28:29], 0, v[146:147]
	v_cvt_pk_bf16_f32 v27, v30, v27
	global_store_dwordx4 v[36:37], v[24:27], off offset:1024
	global_load_dwordx4 v[28:31], v[46:47], off offset:256
	s_nop 0
	v_mov_b32_e32 v24, v232
	v_mov_b32_e32 v25, v233
	v_mov_b32_e32 v26, v234
	v_mov_b32_e32 v27, v235
	v_mov_b32_e32 v32, v236
	v_mov_b32_e32 v33, v237
	v_mov_b32_e32 v34, v238
	v_mov_b32_e32 v35, v239
	s_waitcnt vmcnt(0) lgkmcnt(0)
	v_add_f32_e32 v20, v20, v24
	v_mul_f32_e32 v20, 0xbfb8aa3b, v20
	v_exp_f32_e32 v20, v20
	v_add_f32_e32 v16, v16, v32
	v_mul_f32_e32 v16, 0xbfb8aa3b, v16
	v_exp_f32_e32 v16, v16
	v_add_f32_e32 v20, 1.0, v20
	v_add_f32_e32 v16, 1.0, v16
	v_add_f32_e32 v21, v21, v25
	v_mul_f32_e32 v21, 0xbfb8aa3b, v21
	v_rcp_f32_e32 v20, v20
	v_exp_f32_e32 v21, v21
	v_lshlrev_b32_e32 v38, 16, v28
	v_mul_f32_e32 v20, v20, v38
	v_add_f32_e32 v21, 1.0, v21
	v_add_f32_e32 v17, v17, v33
	v_lshlrev_b32_e32 v39, 16, v30
	v_rcp_f32_e32 v16, v16
	v_mul_f32_e32 v17, 0xbfb8aa3b, v17
	v_mul_f32_e32 v25, v16, v39
	v_exp_f32_e32 v17, v17
	s_nop 0
	v_add_f32_e32 v17, 1.0, v17
	v_add_f32_e32 v22, v22, v26
	v_mul_f32_e32 v22, 0xbfb8aa3b, v22
	v_exp_f32_e32 v22, v22
	v_rcp_f32_e32 v16, v21
	v_and_b32_e32 v28, 0xffff0000, v28
	v_mul_f32_e32 v16, v16, v28
	v_add_f32_e32 v22, 1.0, v22
	v_add_f32_e32 v18, v18, v34
	v_and_b32_e32 v30, 0xffff0000, v30
	v_rcp_f32_e32 v17, v17
	v_mul_f32_e32 v18, 0xbfb8aa3b, v18
	v_mul_f32_e32 v21, v17, v30
	v_exp_f32_e32 v18, v18
	s_nop 0
	v_add_f32_e32 v18, 1.0, v18
	v_add_f32_e32 v23, v23, v27
	v_mul_f32_e32 v23, 0xbfb8aa3b, v23
	v_rcp_f32_e32 v17, v22
	v_exp_f32_e32 v23, v23
	v_lshlrev_b32_e32 v24, 16, v29
	v_mul_f32_e32 v17, v17, v24
	v_add_f32_e32 v23, 1.0, v23
	v_add_f32_e32 v19, v19, v35
	v_lshlrev_b32_e32 v42, 16, v31
	v_rcp_f32_e32 v18, v18
	v_mul_f32_e32 v19, 0xbfb8aa3b, v19
	v_mul_f32_e32 v22, v18, v42
	v_exp_f32_e32 v19, v19
	s_nop 0
	v_add_f32_e32 v19, 1.0, v19
	v_rcp_f32_e32 v18, v23
	v_and_b32_e32 v29, 0xffff0000, v29
	v_add_u32_e32 v28, 0xb0, v148
	v_mul_f32_e32 v18, v18, v29
	v_ashrrev_i32_e32 v29, 31, v28
	v_and_b32_e32 v31, 0xffff0000, v31
	v_rcp_f32_e32 v19, v19
	v_cvt_pk_bf16_f32 v16, v20, v16
	v_cvt_pk_bf16_f32 v17, v17, v18
	v_cvt_pk_bf16_f32 v18, v25, v21
	v_lshlrev_b64 v[20:21], 10, v[28:29]
	v_mul_f32_e32 v19, v19, v31
	v_lshl_add_u64 v[20:21], s[60:61], 0, v[20:21]
	v_cvt_pk_bf16_f32 v19, v22, v19
	v_lshl_add_u64 v[30:31], v[20:21], 0, v[146:147]
	global_store_dwordx4 v[36:37], v[16:19], off offset:1280
	global_load_dwordx4 v[20:23], v[30:31], off
	s_nop 0
	v_mov_b32_e32 v16, v224
	v_mov_b32_e32 v17, v225
	v_mov_b32_e32 v18, v226
	v_mov_b32_e32 v19, v227
	v_mov_b32_e32 v24, v228
	v_mov_b32_e32 v25, v229
	v_mov_b32_e32 v26, v230
	v_mov_b32_e32 v27, v231
	v_lshlrev_b64 v[28:29], 11, v[28:29]
	s_waitcnt vmcnt(0) lgkmcnt(0)
	v_add_f32_e32 v12, v12, v16
	v_mul_f32_e32 v12, 0xbfb8aa3b, v12
	v_exp_f32_e32 v12, v12
	v_add_f32_e32 v8, v8, v24
	v_mul_f32_e32 v8, 0xbfb8aa3b, v8
	v_exp_f32_e32 v8, v8
	v_add_f32_e32 v12, 1.0, v12
	v_add_f32_e32 v8, 1.0, v8
	v_add_f32_e32 v13, v13, v17
	v_mul_f32_e32 v13, 0xbfb8aa3b, v13
	v_rcp_f32_e32 v12, v12
	v_exp_f32_e32 v13, v13
	v_lshlrev_b32_e32 v32, 16, v20
	v_mul_f32_e32 v12, v12, v32
	v_add_f32_e32 v13, 1.0, v13
	v_add_f32_e32 v9, v9, v25
	v_lshlrev_b32_e32 v33, 16, v22
	v_rcp_f32_e32 v8, v8
	v_mul_f32_e32 v9, 0xbfb8aa3b, v9
	v_mul_f32_e32 v17, v8, v33
	v_exp_f32_e32 v9, v9
	s_nop 0
	v_add_f32_e32 v9, 1.0, v9
	v_add_f32_e32 v14, v14, v18
	v_mul_f32_e32 v14, 0xbfb8aa3b, v14
	v_exp_f32_e32 v14, v14
	v_rcp_f32_e32 v8, v13
	v_and_b32_e32 v20, 0xffff0000, v20
	v_mul_f32_e32 v8, v8, v20
	v_add_f32_e32 v14, 1.0, v14
	v_add_f32_e32 v10, v10, v26
	v_and_b32_e32 v22, 0xffff0000, v22
	v_rcp_f32_e32 v9, v9
	v_mul_f32_e32 v10, 0xbfb8aa3b, v10
	v_mul_f32_e32 v13, v9, v22
	v_exp_f32_e32 v10, v10
	s_nop 0
	v_add_f32_e32 v10, 1.0, v10
	v_add_f32_e32 v15, v15, v19
	v_mul_f32_e32 v15, 0xbfb8aa3b, v15
	v_rcp_f32_e32 v9, v14
	v_exp_f32_e32 v15, v15
	v_lshlrev_b32_e32 v16, 16, v21
	v_mul_f32_e32 v9, v9, v16
	v_add_f32_e32 v15, 1.0, v15
	v_add_f32_e32 v11, v11, v27
	v_lshlrev_b32_e32 v36, 16, v23
	v_rcp_f32_e32 v10, v10
	v_mul_f32_e32 v11, 0xbfb8aa3b, v11
	v_mul_f32_e32 v14, v10, v36
	v_exp_f32_e32 v11, v11
	s_nop 0
	v_add_f32_e32 v11, 1.0, v11
	v_rcp_f32_e32 v10, v15
	v_and_b32_e32 v21, 0xffff0000, v21
	v_mul_f32_e32 v10, v10, v21
	v_and_b32_e32 v23, 0xffff0000, v23
	v_rcp_f32_e32 v11, v11
	v_cvt_pk_bf16_f32 v8, v12, v8
	v_cvt_pk_bf16_f32 v9, v9, v10
	v_cvt_pk_bf16_f32 v10, v17, v13
	v_lshl_add_u64 v[12:13], s[48:49], 0, v[28:29]
	v_mul_f32_e32 v11, v11, v23
	v_lshl_add_u64 v[20:21], v[12:13], 0, v[146:147]
	v_cvt_pk_bf16_f32 v11, v14, v11
	global_store_dwordx4 v[20:21], v[8:11], off offset:1024
	global_load_dwordx4 v[12:15], v[30:31], off offset:256
	s_nop 0
	v_mov_b32_e32 v8, v232
	v_mov_b32_e32 v9, v233
	v_mov_b32_e32 v10, v234
	v_mov_b32_e32 v11, v235
	v_mov_b32_e32 v16, v236
	v_mov_b32_e32 v17, v237
	v_mov_b32_e32 v18, v238
	v_mov_b32_e32 v19, v239
	s_waitcnt vmcnt(0) lgkmcnt(0)
	v_add_f32_e32 v4, v4, v8
	v_mul_f32_e32 v4, 0xbfb8aa3b, v4
	v_exp_f32_e32 v4, v4
	v_add_f32_e32 v0, v0, v16
	v_mul_f32_e32 v0, 0xbfb8aa3b, v0
	v_exp_f32_e32 v0, v0
	v_add_f32_e32 v4, 1.0, v4
	v_add_f32_e32 v0, 1.0, v0
	v_add_f32_e32 v5, v5, v9
	v_mul_f32_e32 v5, 0xbfb8aa3b, v5
	v_rcp_f32_e32 v4, v4
	v_exp_f32_e32 v5, v5
	v_lshlrev_b32_e32 v22, 16, v12
	v_mul_f32_e32 v4, v4, v22
	v_add_f32_e32 v5, 1.0, v5
	v_add_f32_e32 v1, v1, v17
	v_lshlrev_b32_e32 v23, 16, v14
	v_rcp_f32_e32 v0, v0
	v_mul_f32_e32 v1, 0xbfb8aa3b, v1
	v_mul_f32_e32 v9, v0, v23
	v_exp_f32_e32 v1, v1
	s_nop 0
	v_add_f32_e32 v1, 1.0, v1
	v_add_f32_e32 v6, v6, v10
	v_mul_f32_e32 v6, 0xbfb8aa3b, v6
	v_exp_f32_e32 v6, v6
	v_rcp_f32_e32 v0, v5
	v_and_b32_e32 v12, 0xffff0000, v12
	v_mul_f32_e32 v0, v0, v12
	v_add_f32_e32 v6, 1.0, v6
	v_add_f32_e32 v2, v2, v18
	v_and_b32_e32 v14, 0xffff0000, v14
	v_rcp_f32_e32 v1, v1
	v_mul_f32_e32 v2, 0xbfb8aa3b, v2
	v_mul_f32_e32 v5, v1, v14
	v_exp_f32_e32 v2, v2
	s_nop 0
	v_add_f32_e32 v2, 1.0, v2
	v_add_f32_e32 v7, v7, v11
	v_mul_f32_e32 v7, 0xbfb8aa3b, v7
	v_rcp_f32_e32 v1, v6
	v_exp_f32_e32 v7, v7
	v_lshlrev_b32_e32 v8, 16, v13
	v_mul_f32_e32 v1, v1, v8
	v_add_f32_e32 v7, 1.0, v7
	v_add_f32_e32 v3, v3, v19
	v_lshlrev_b32_e32 v26, 16, v15
	v_rcp_f32_e32 v2, v2
	v_mul_f32_e32 v3, 0xbfb8aa3b, v3
	v_mul_f32_e32 v6, v2, v26
	v_exp_f32_e32 v3, v3
	s_nop 0
	v_add_f32_e32 v3, 1.0, v3
	v_rcp_f32_e32 v2, v7
	v_and_b32_e32 v13, 0xffff0000, v13
	v_and_b32_e32 v15, 0xffff0000, v15
	v_rcp_f32_e32 v3, v3
	v_mul_f32_e32 v2, v2, v13
	v_mul_f32_e32 v3, v3, v15
	s_andn2_b64 vcc, exec, s[4:5]
	s_mov_b64 s[0:1], -1
	v_cvt_pk_bf16_f32 v0, v4, v0
	v_cvt_pk_bf16_f32 v1, v1, v2
	v_cvt_pk_bf16_f32 v2, v9, v5
	v_cvt_pk_bf16_f32 v3, v6, v3
	global_store_dwordx4 v[20:21], v[0:3], off offset:1280
	s_cbranch_vccnz .LBB0_1424
	s_andn2_b64 vcc, exec, s[14:15]
	s_cbranch_vccnz .LBB0_1423
	s_barrier
	s_branch .LBB0_1423

.LBB0_1455:
	s_or_b64 exec, exec, s[0:1]
	v_mov_b32_e32 v66, 0xf149f2ca
	v_mov_b32_e32 v67, 0xf149f2ca
	ds_read_b32 v176, v82 offset:496
	ds_read_b32 v177, v83 offset:496
	ds_read_b32 v178, v88 offset:496
	ds_read_b32 v179, v90 offset:496
	ds_read_b32 v180, v91 offset:496
	ds_read_b32 v181, v92 offset:496
	ds_read_b32 v182, v93 offset:496
	ds_read_b32 v183, v94 offset:496
	s_waitcnt lgkmcnt(0)
	s_and_saveexec_b64 s[0:1], vcc
	s_cbranch_execz .LBB0_1457
	v_mov_b32_e32 v97, v176
	s_mov_b32 s34, 0x3e38aa3b
	v_mov_b32_e32 v96, v60
	s_mov_b32 s35, 0x3fb8aa3b
	s_waitcnt lgkmcnt(0)
	v_pk_mul_f32 v[96:97], v[96:97], s[34:35]
	s_nop 0
	v_add_f32_e32 v67, v96, v97
.LBB0_1457:
	s_or_b64 exec, exec, s[0:1]
	s_and_saveexec_b64 s[0:1], s[4:5]
	s_cbranch_execz .LBB0_1459
	v_mov_b32_e32 v97, v177
	s_mov_b32 s34, 0x3e38aa3b
	v_mov_b32_e32 v96, v61
	s_mov_b32 s35, 0x3fb8aa3b
	s_waitcnt lgkmcnt(0)
	v_pk_mul_f32 v[60:61], v[96:97], s[34:35]
	s_nop 0
	v_add_f32_e32 v66, v60, v61
.LBB0_1459:
	s_or_b64 exec, exec, s[0:1]
	v_mov_b32_e32 v60, 0xf149f2ca
	v_mov_b32_e32 v61, 0xf149f2ca
	s_and_saveexec_b64 s[0:1], s[6:7]
	s_cbranch_execz .LBB0_1461
	v_mov_b32_e32 v97, v178
	s_mov_b32 s34, 0x3e38aa3b
	v_mov_b32_e32 v96, v62
	s_mov_b32 s35, 0x3fb8aa3b
	s_waitcnt lgkmcnt(0)
	v_pk_mul_f32 v[96:97], v[96:97], s[34:35]
	s_nop 0
	v_add_f32_e32 v61, v96, v97
.LBB0_1461:
	s_or_b64 exec, exec, s[0:1]
	s_and_saveexec_b64 s[0:1], s[8:9]
	s_cbranch_execz .LBB0_1463
	v_mov_b32_e32 v97, v179
	s_mov_b32 s34, 0x3e38aa3b
	v_mov_b32_e32 v96, v63
	s_mov_b32 s35, 0x3fb8aa3b
	s_waitcnt lgkmcnt(0)
	v_pk_mul_f32 v[62:63], v[96:97], s[34:35]
	s_nop 0
	v_add_f32_e32 v60, v62, v63
.LBB0_1463:
	s_or_b64 exec, exec, s[0:1]
	v_mov_b32_e32 v62, 0xf149f2ca
	v_mov_b32_e32 v63, 0xf149f2ca
	s_and_saveexec_b64 s[0:1], s[10:11]
	s_cbranch_execz .LBB0_1465
	v_mov_b32_e32 v97, v180
	s_mov_b32 s34, 0x3e38aa3b
	v_mov_b32_e32 v96, v56
	s_mov_b32 s35, 0x3fb8aa3b
	s_waitcnt lgkmcnt(0)
	v_pk_mul_f32 v[96:97], v[96:97], s[34:35]
	s_nop 0
	v_add_f32_e32 v63, v96, v97
.LBB0_1465:
	s_or_b64 exec, exec, s[0:1]
	s_and_saveexec_b64 s[0:1], s[12:13]
	s_cbranch_execz .LBB0_1467
	v_mov_b32_e32 v97, v181
	s_mov_b32 s34, 0x3e38aa3b
	v_mov_b32_e32 v96, v57
	s_mov_b32 s35, 0x3fb8aa3b
	s_waitcnt lgkmcnt(0)
	v_pk_mul_f32 v[56:57], v[96:97], s[34:35]
	s_nop 0
	v_add_f32_e32 v62, v56, v57
.LBB0_1467:
	s_or_b64 exec, exec, s[0:1]
	v_mov_b32_e32 v56, 0xf149f2ca
	v_mov_b32_e32 v89, 0xf149f2ca
	s_and_saveexec_b64 s[0:1], s[14:15]
	s_cbranch_execz .LBB0_1469
	v_mov_b32_e32 v97, v182
	s_mov_b32 s34, 0x3e38aa3b
	v_mov_b32_e32 v96, v58
	s_mov_b32 s35, 0x3fb8aa3b
	s_waitcnt lgkmcnt(0)
	v_pk_mul_f32 v[96:97], v[96:97], s[34:35]
	s_nop 0
	v_add_f32_e32 v89, v96, v97
.LBB0_1469:
	s_or_b64 exec, exec, s[0:1]
	s_and_saveexec_b64 s[0:1], s[16:17]
	s_cbranch_execz .LBB0_1471
	v_mov_b32_e32 v57, v183
	s_mov_b32 s34, 0x3e38aa3b
	v_mov_b32_e32 v56, v59
	s_mov_b32 s35, 0x3fb8aa3b
	s_waitcnt lgkmcnt(0)
	v_pk_mul_f32 v[56:57], v[56:57], s[34:35]
	s_nop 0
	v_add_f32_e32 v56, v56, v57
.LBB0_1471:
	s_or_b64 exec, exec, s[0:1]
	v_mov_b32_e32 v57, 0xf149f2ca
	v_mov_b32_e32 v58, 0xf149f2ca
	ds_read_b32 v176, v82 offset:620
	ds_read_b32 v177, v83 offset:620
	ds_read_b32 v178, v88 offset:620
	ds_read_b32 v179, v90 offset:620
	ds_read_b32 v180, v91 offset:620
	ds_read_b32 v181, v92 offset:620
	ds_read_b32 v182, v93 offset:620
	ds_read_b32 v183, v94 offset:620
	s_waitcnt lgkmcnt(0)
	s_and_saveexec_b64 s[0:1], vcc
	s_cbranch_execz .LBB0_1473
	v_mov_b32_e32 v59, v176
	s_mov_b32 s34, 0x3e38aa3b
	v_mov_b32_e32 v58, v52
	s_mov_b32 s35, 0x3fb8aa3b
	s_waitcnt lgkmcnt(0)
	v_pk_mul_f32 v[58:59], v[58:59], s[34:35]
	s_nop 0
	v_add_f32_e32 v58, v58, v59
.LBB0_1473:
	s_or_b64 exec, exec, s[0:1]
	s_and_saveexec_b64 s[0:1], s[4:5]
	s_cbranch_execz .LBB0_1475
	v_mov_b32_e32 v97, v177
	s_mov_b32 s34, 0x3e38aa3b
	v_mov_b32_e32 v96, v53
	s_mov_b32 s35, 0x3fb8aa3b
	s_waitcnt lgkmcnt(0)
	v_pk_mul_f32 v[52:53], v[96:97], s[34:35]
	s_nop 0
	v_add_f32_e32 v57, v52, v53
.LBB0_1475:
	s_or_b64 exec, exec, s[0:1]
	v_mov_b32_e32 v52, 0xf149f2ca
	v_mov_b32_e32 v53, 0xf149f2ca
	s_and_saveexec_b64 s[0:1], s[6:7]
	s_cbranch_execz .LBB0_1477
	v_mov_b32_e32 v97, v178
	s_mov_b32 s34, 0x3e38aa3b
	v_mov_b32_e32 v96, v54
	s_mov_b32 s35, 0x3fb8aa3b
	s_waitcnt lgkmcnt(0)
	v_pk_mul_f32 v[96:97], v[96:97], s[34:35]
	s_nop 0
	v_add_f32_e32 v53, v96, v97
.LBB0_1477:
	s_or_b64 exec, exec, s[0:1]
	s_and_saveexec_b64 s[0:1], s[8:9]
	s_cbranch_execz .LBB0_1479
	v_mov_b32_e32 v97, v179
	s_mov_b32 s34, 0x3e38aa3b
	v_mov_b32_e32 v96, v55
	s_mov_b32 s35, 0x3fb8aa3b
	s_waitcnt lgkmcnt(0)
	v_pk_mul_f32 v[54:55], v[96:97], s[34:35]
	s_nop 0
	v_add_f32_e32 v52, v54, v55
.LBB0_1479:
	s_or_b64 exec, exec, s[0:1]
	v_mov_b32_e32 v54, 0xf149f2ca
	v_mov_b32_e32 v55, 0xf149f2ca
	s_and_saveexec_b64 s[0:1], s[10:11]
	s_cbranch_execz .LBB0_1481
	v_mov_b32_e32 v97, v180
	s_mov_b32 s34, 0x3e38aa3b
	v_mov_b32_e32 v96, v48
	s_mov_b32 s35, 0x3fb8aa3b
	s_waitcnt lgkmcnt(0)
	v_pk_mul_f32 v[96:97], v[96:97], s[34:35]
	s_nop 0
	v_add_f32_e32 v55, v96, v97
.LBB0_1481:
	s_or_b64 exec, exec, s[0:1]
	s_and_saveexec_b64 s[0:1], s[12:13]
	s_cbranch_execz .LBB0_1483
	v_mov_b32_e32 v97, v181
	s_mov_b32 s34, 0x3e38aa3b
	v_mov_b32_e32 v96, v49
	s_mov_b32 s35, 0x3fb8aa3b
	s_waitcnt lgkmcnt(0)
	v_pk_mul_f32 v[48:49], v[96:97], s[34:35]
	s_nop 0
	v_add_f32_e32 v54, v48, v49
.LBB0_1483:
	s_or_b64 exec, exec, s[0:1]
	v_mov_b32_e32 v48, 0xf149f2ca
	v_mov_b32_e32 v59, 0xf149f2ca
	s_and_saveexec_b64 s[0:1], s[14:15]
	s_cbranch_execz .LBB0_1485
	v_mov_b32_e32 v97, v182
	s_mov_b32 s34, 0x3e38aa3b
	v_mov_b32_e32 v96, v50
	s_mov_b32 s35, 0x3fb8aa3b
	s_waitcnt lgkmcnt(0)
	v_pk_mul_f32 v[96:97], v[96:97], s[34:35]
	s_nop 0
	v_add_f32_e32 v59, v96, v97
.LBB0_1485:
	s_or_b64 exec, exec, s[0:1]
	s_and_saveexec_b64 s[0:1], s[16:17]
	s_cbranch_execz .LBB0_1487
	v_mov_b32_e32 v49, v183
	s_mov_b32 s34, 0x3e38aa3b
	v_mov_b32_e32 v48, v51
	s_mov_b32 s35, 0x3fb8aa3b
	s_waitcnt lgkmcnt(0)
	v_pk_mul_f32 v[48:49], v[48:49], s[34:35]
	s_nop 0
	v_add_f32_e32 v48, v48, v49
.LBB0_1487:
	s_or_b64 exec, exec, s[0:1]
	v_mov_b32_e32 v49, 0xf149f2ca
	v_mov_b32_e32 v50, 0xf149f2ca
	ds_read_b32 v176, v82 offset:744
	ds_read_b32 v177, v83 offset:744
	ds_read_b32 v178, v88 offset:744
	ds_read_b32 v179, v90 offset:744
	ds_read_b32 v180, v91 offset:744
	ds_read_b32 v181, v92 offset:744
	ds_read_b32 v182, v93 offset:744
	ds_read_b32 v183, v94 offset:744
	s_waitcnt lgkmcnt(0)
	s_and_saveexec_b64 s[0:1], vcc
	s_cbranch_execz .LBB0_1489
	v_mov_b32_e32 v51, v176
	s_mov_b32 s34, 0x3e38aa3b
	v_mov_b32_e32 v50, v44
	s_mov_b32 s35, 0x3fb8aa3b
	s_waitcnt lgkmcnt(0)
	v_pk_mul_f32 v[50:51], v[50:51], s[34:35]
	s_nop 0
	v_add_f32_e32 v50, v50, v51
.LBB0_1489:
	s_or_b64 exec, exec, s[0:1]
	s_and_saveexec_b64 s[0:1], s[4:5]
	s_cbranch_execz .LBB0_1491
	v_mov_b32_e32 v97, v177
	s_mov_b32 s34, 0x3e38aa3b
	v_mov_b32_e32 v96, v45
	s_mov_b32 s35, 0x3fb8aa3b
	s_waitcnt lgkmcnt(0)
	v_pk_mul_f32 v[44:45], v[96:97], s[34:35]
	s_nop 0
	v_add_f32_e32 v49, v44, v45
.LBB0_1491:
	s_or_b64 exec, exec, s[0:1]
	v_mov_b32_e32 v44, 0xf149f2ca
	v_mov_b32_e32 v45, 0xf149f2ca
	s_and_saveexec_b64 s[0:1], s[6:7]
	s_cbranch_execz .LBB0_1493
	v_mov_b32_e32 v97, v178
	s_mov_b32 s34, 0x3e38aa3b
	v_mov_b32_e32 v96, v46
	s_mov_b32 s35, 0x3fb8aa3b
	s_waitcnt lgkmcnt(0)
	v_pk_mul_f32 v[96:97], v[96:97], s[34:35]
	s_nop 0
	v_add_f32_e32 v45, v96, v97
.LBB0_1493:
	s_or_b64 exec, exec, s[0:1]
	s_and_saveexec_b64 s[0:1], s[8:9]
	s_cbranch_execz .LBB0_1495
	v_mov_b32_e32 v97, v179
	s_mov_b32 s34, 0x3e38aa3b
	v_mov_b32_e32 v96, v47
	s_mov_b32 s35, 0x3fb8aa3b
	s_waitcnt lgkmcnt(0)
	v_pk_mul_f32 v[46:47], v[96:97], s[34:35]
	s_nop 0
	v_add_f32_e32 v44, v46, v47
.LBB0_1495:
	s_or_b64 exec, exec, s[0:1]
	v_mov_b32_e32 v46, 0xf149f2ca
	v_mov_b32_e32 v47, 0xf149f2ca
	s_and_saveexec_b64 s[0:1], s[10:11]
	s_cbranch_execz .LBB0_1497
	v_mov_b32_e32 v97, v180
	s_mov_b32 s34, 0x3e38aa3b
	v_mov_b32_e32 v96, v40
	s_mov_b32 s35, 0x3fb8aa3b
	s_waitcnt lgkmcnt(0)
	v_pk_mul_f32 v[96:97], v[96:97], s[34:35]
	s_nop 0
	v_add_f32_e32 v47, v96, v97
.LBB0_1497:
	s_or_b64 exec, exec, s[0:1]
	s_and_saveexec_b64 s[0:1], s[12:13]
	s_cbranch_execz .LBB0_1499
	v_mov_b32_e32 v97, v181
	s_mov_b32 s34, 0x3e38aa3b
	v_mov_b32_e32 v96, v41
	s_mov_b32 s35, 0x3fb8aa3b
	s_waitcnt lgkmcnt(0)
	v_pk_mul_f32 v[40:41], v[96:97], s[34:35]
	s_nop 0
	v_add_f32_e32 v46, v40, v41
.LBB0_1499:
	s_or_b64 exec, exec, s[0:1]
	v_mov_b32_e32 v40, 0xf149f2ca
	v_mov_b32_e32 v51, 0xf149f2ca
	s_and_saveexec_b64 s[0:1], s[14:15]
	s_cbranch_execz .LBB0_1501
	v_mov_b32_e32 v97, v182
	s_mov_b32 s34, 0x3e38aa3b
	v_mov_b32_e32 v96, v42
	s_mov_b32 s35, 0x3fb8aa3b
	s_waitcnt lgkmcnt(0)
	v_pk_mul_f32 v[96:97], v[96:97], s[34:35]
	s_nop 0
	v_add_f32_e32 v51, v96, v97
.LBB0_1501:
	s_or_b64 exec, exec, s[0:1]
	s_and_saveexec_b64 s[0:1], s[16:17]
	s_cbranch_execz .LBB0_1503
	v_mov_b32_e32 v41, v183
	s_mov_b32 s34, 0x3e38aa3b
	v_mov_b32_e32 v40, v43
	s_mov_b32 s35, 0x3fb8aa3b
	s_waitcnt lgkmcnt(0)
	v_pk_mul_f32 v[40:41], v[40:41], s[34:35]
	s_nop 0
	v_add_f32_e32 v40, v40, v41
.LBB0_1503:
	s_or_b64 exec, exec, s[0:1]
	v_mov_b32_e32 v41, 0xf149f2ca
	v_mov_b32_e32 v42, 0xf149f2ca
	ds_read_b32 v176, v82 offset:868
	ds_read_b32 v177, v83 offset:868
	ds_read_b32 v178, v88 offset:868
	ds_read_b32 v179, v90 offset:868
	ds_read_b32 v180, v91 offset:868
	ds_read_b32 v181, v92 offset:868
	ds_read_b32 v182, v93 offset:868
	ds_read_b32 v183, v94 offset:868
	s_waitcnt lgkmcnt(0)
	s_and_saveexec_b64 s[0:1], vcc
	s_cbranch_execz .LBB0_1505
	v_mov_b32_e32 v43, v176
	s_mov_b32 s34, 0x3e38aa3b
	v_mov_b32_e32 v42, v36
	s_mov_b32 s35, 0x3fb8aa3b
	s_waitcnt lgkmcnt(0)
	v_pk_mul_f32 v[42:43], v[42:43], s[34:35]
	s_nop 0
	v_add_f32_e32 v42, v42, v43
.LBB0_1505:
	s_or_b64 exec, exec, s[0:1]
	s_and_saveexec_b64 s[0:1], s[4:5]
	s_cbranch_execz .LBB0_1507
	v_mov_b32_e32 v97, v177
	s_mov_b32 s34, 0x3e38aa3b
	v_mov_b32_e32 v96, v37
	s_mov_b32 s35, 0x3fb8aa3b
	s_waitcnt lgkmcnt(0)
	v_pk_mul_f32 v[36:37], v[96:97], s[34:35]
	s_nop 0
	v_add_f32_e32 v41, v36, v37
.LBB0_1507:
	s_or_b64 exec, exec, s[0:1]
	v_mov_b32_e32 v36, 0xf149f2ca
	v_mov_b32_e32 v37, 0xf149f2ca
	s_and_saveexec_b64 s[0:1], s[6:7]
	s_cbranch_execz .LBB0_1509
	v_mov_b32_e32 v97, v178
	s_mov_b32 s34, 0x3e38aa3b
	v_mov_b32_e32 v96, v38
	s_mov_b32 s35, 0x3fb8aa3b
	s_waitcnt lgkmcnt(0)
	v_pk_mul_f32 v[96:97], v[96:97], s[34:35]
	s_nop 0
	v_add_f32_e32 v37, v96, v97
.LBB0_1509:
	s_or_b64 exec, exec, s[0:1]
	s_and_saveexec_b64 s[0:1], s[8:9]
	s_cbranch_execz .LBB0_1511
	v_mov_b32_e32 v97, v179
	s_mov_b32 s34, 0x3e38aa3b
	v_mov_b32_e32 v96, v39
	s_mov_b32 s35, 0x3fb8aa3b
	s_waitcnt lgkmcnt(0)
	v_pk_mul_f32 v[38:39], v[96:97], s[34:35]
	s_nop 0
	v_add_f32_e32 v36, v38, v39
.LBB0_1511:
	s_or_b64 exec, exec, s[0:1]
	v_mov_b32_e32 v38, 0xf149f2ca
	v_mov_b32_e32 v39, 0xf149f2ca
	s_and_saveexec_b64 s[0:1], s[10:11]
	s_cbranch_execz .LBB0_1513
	v_mov_b32_e32 v97, v180
	s_mov_b32 s34, 0x3e38aa3b
	v_mov_b32_e32 v96, v32
	s_mov_b32 s35, 0x3fb8aa3b
	s_waitcnt lgkmcnt(0)
	v_pk_mul_f32 v[96:97], v[96:97], s[34:35]
	s_nop 0
	v_add_f32_e32 v39, v96, v97
.LBB0_1513:
	s_or_b64 exec, exec, s[0:1]
	s_and_saveexec_b64 s[0:1], s[12:13]
	s_cbranch_execz .LBB0_1515
	v_mov_b32_e32 v97, v181
	s_mov_b32 s34, 0x3e38aa3b
	v_mov_b32_e32 v96, v33
	s_mov_b32 s35, 0x3fb8aa3b
	s_waitcnt lgkmcnt(0)
	v_pk_mul_f32 v[32:33], v[96:97], s[34:35]
	s_nop 0
	v_add_f32_e32 v38, v32, v33
.LBB0_1515:
	s_or_b64 exec, exec, s[0:1]
	v_mov_b32_e32 v32, 0xf149f2ca
	v_mov_b32_e32 v43, 0xf149f2ca
	s_and_saveexec_b64 s[0:1], s[14:15]
	s_cbranch_execz .LBB0_1517
	v_mov_b32_e32 v97, v182
	s_mov_b32 s34, 0x3e38aa3b
	v_mov_b32_e32 v96, v34
	s_mov_b32 s35, 0x3fb8aa3b
	s_waitcnt lgkmcnt(0)
	v_pk_mul_f32 v[96:97], v[96:97], s[34:35]
	s_nop 0
	v_add_f32_e32 v43, v96, v97
.LBB0_1517:
	s_or_b64 exec, exec, s[0:1]
	s_and_saveexec_b64 s[0:1], s[16:17]
	s_cbranch_execz .LBB0_1519
	v_mov_b32_e32 v33, v183
	s_mov_b32 s34, 0x3e38aa3b
	v_mov_b32_e32 v32, v35
	s_mov_b32 s35, 0x3fb8aa3b
	s_waitcnt lgkmcnt(0)
	v_pk_mul_f32 v[32:33], v[32:33], s[34:35]
	s_nop 0
	v_add_f32_e32 v32, v32, v33
.LBB0_1519:
	s_or_b64 exec, exec, s[0:1]
	v_mov_b32_e32 v33, 0xf149f2ca
	v_mov_b32_e32 v34, 0xf149f2ca
	ds_read_b32 v176, v82 offset:992
	ds_read_b32 v177, v83 offset:992
	ds_read_b32 v178, v88 offset:992
	ds_read_b32 v179, v90 offset:992
	ds_read_b32 v180, v91 offset:992
	ds_read_b32 v181, v92 offset:992
	ds_read_b32 v182, v93 offset:992
	ds_read_b32 v183, v94 offset:992
	s_waitcnt lgkmcnt(0)
	s_and_saveexec_b64 s[0:1], vcc
	s_cbranch_execz .LBB0_1521
	v_mov_b32_e32 v35, v176
	s_mov_b32 s34, 0x3e38aa3b
	v_mov_b32_e32 v34, v28
	s_mov_b32 s35, 0x3fb8aa3b
	s_waitcnt lgkmcnt(0)
	v_pk_mul_f32 v[34:35], v[34:35], s[34:35]
	s_nop 0
	v_add_f32_e32 v34, v34, v35
.LBB0_1521:
	s_or_b64 exec, exec, s[0:1]
	s_and_saveexec_b64 s[0:1], s[4:5]
	s_cbranch_execz .LBB0_1523
	v_mov_b32_e32 v97, v177
	s_mov_b32 s34, 0x3e38aa3b
	v_mov_b32_e32 v96, v29
	s_mov_b32 s35, 0x3fb8aa3b
	s_waitcnt lgkmcnt(0)
	v_pk_mul_f32 v[28:29], v[96:97], s[34:35]
	s_nop 0
	v_add_f32_e32 v33, v28, v29
.LBB0_1523:
	s_or_b64 exec, exec, s[0:1]
	v_mov_b32_e32 v28, 0xf149f2ca
	v_mov_b32_e32 v29, 0xf149f2ca
	s_and_saveexec_b64 s[0:1], s[6:7]
	s_cbranch_execz .LBB0_1525
	v_mov_b32_e32 v97, v178
	s_mov_b32 s34, 0x3e38aa3b
	v_mov_b32_e32 v96, v30
	s_mov_b32 s35, 0x3fb8aa3b
	s_waitcnt lgkmcnt(0)
	v_pk_mul_f32 v[96:97], v[96:97], s[34:35]
	s_nop 0
	v_add_f32_e32 v29, v96, v97
.LBB0_1525:
	s_or_b64 exec, exec, s[0:1]
	s_and_saveexec_b64 s[0:1], s[8:9]
	s_cbranch_execz .LBB0_1527
	v_mov_b32_e32 v97, v179
	s_mov_b32 s34, 0x3e38aa3b
	v_mov_b32_e32 v96, v31
	s_mov_b32 s35, 0x3fb8aa3b
	s_waitcnt lgkmcnt(0)
	v_pk_mul_f32 v[30:31], v[96:97], s[34:35]
	s_nop 0
	v_add_f32_e32 v28, v30, v31
.LBB0_1527:
	s_or_b64 exec, exec, s[0:1]
	v_mov_b32_e32 v30, 0xf149f2ca
	v_mov_b32_e32 v31, 0xf149f2ca
	s_and_saveexec_b64 s[0:1], s[10:11]
	s_cbranch_execz .LBB0_1529
	v_mov_b32_e32 v97, v180
	s_mov_b32 s34, 0x3e38aa3b
	v_mov_b32_e32 v96, v24
	s_mov_b32 s35, 0x3fb8aa3b
	s_waitcnt lgkmcnt(0)
	v_pk_mul_f32 v[96:97], v[96:97], s[34:35]
	s_nop 0
	v_add_f32_e32 v31, v96, v97
.LBB0_1529:
	s_or_b64 exec, exec, s[0:1]
	s_and_saveexec_b64 s[0:1], s[12:13]
	s_cbranch_execz .LBB0_1531
	v_mov_b32_e32 v97, v181
	s_mov_b32 s34, 0x3e38aa3b
	v_mov_b32_e32 v96, v25
	s_mov_b32 s35, 0x3fb8aa3b
	s_waitcnt lgkmcnt(0)
	v_pk_mul_f32 v[24:25], v[96:97], s[34:35]
	s_nop 0
	v_add_f32_e32 v30, v24, v25
.LBB0_1531:
	s_or_b64 exec, exec, s[0:1]
	v_mov_b32_e32 v24, 0xf149f2ca
	v_mov_b32_e32 v35, 0xf149f2ca
	s_and_saveexec_b64 s[0:1], s[14:15]
	s_cbranch_execz .LBB0_1533
	v_mov_b32_e32 v97, v182
	s_mov_b32 s34, 0x3e38aa3b
	v_mov_b32_e32 v96, v26
	s_mov_b32 s35, 0x3fb8aa3b
	s_waitcnt lgkmcnt(0)
	v_pk_mul_f32 v[96:97], v[96:97], s[34:35]
	s_nop 0
	v_add_f32_e32 v35, v96, v97
.LBB0_1533:
	s_or_b64 exec, exec, s[0:1]
	s_and_saveexec_b64 s[0:1], s[16:17]
	s_cbranch_execz .LBB0_1535
	v_mov_b32_e32 v25, v183
	s_mov_b32 s34, 0x3e38aa3b
	v_mov_b32_e32 v24, v27
	s_mov_b32 s35, 0x3fb8aa3b
	s_waitcnt lgkmcnt(0)
	v_pk_mul_f32 v[24:25], v[24:25], s[34:35]
	s_nop 0
	v_add_f32_e32 v24, v24, v25
.LBB0_1535:
	s_or_b64 exec, exec, s[0:1]
	v_mov_b32_e32 v25, 0xf149f2ca
	v_mov_b32_e32 v26, 0xf149f2ca
	ds_read_b32 v176, v82 offset:1116
	ds_read_b32 v177, v83 offset:1116
	ds_read_b32 v178, v88 offset:1116
	ds_read_b32 v179, v90 offset:1116
	ds_read_b32 v180, v91 offset:1116
	ds_read_b32 v181, v92 offset:1116
	ds_read_b32 v182, v93 offset:1116
	ds_read_b32 v183, v94 offset:1116
	s_waitcnt lgkmcnt(0)
	s_and_saveexec_b64 s[0:1], vcc
	s_cbranch_execz .LBB0_1537
	v_mov_b32_e32 v27, v176
	s_mov_b32 s34, 0x3e38aa3b
	v_mov_b32_e32 v26, v20
	s_mov_b32 s35, 0x3fb8aa3b
	s_waitcnt lgkmcnt(0)
	v_pk_mul_f32 v[26:27], v[26:27], s[34:35]
	s_nop 0
	v_add_f32_e32 v26, v26, v27
.LBB0_1537:
	s_or_b64 exec, exec, s[0:1]
	s_and_saveexec_b64 s[0:1], s[4:5]
	s_cbranch_execz .LBB0_1539
	v_mov_b32_e32 v97, v177
	s_mov_b32 s34, 0x3e38aa3b
	v_mov_b32_e32 v96, v21
	s_mov_b32 s35, 0x3fb8aa3b
	s_waitcnt lgkmcnt(0)
	v_pk_mul_f32 v[20:21], v[96:97], s[34:35]
	s_nop 0
	v_add_f32_e32 v25, v20, v21
.LBB0_1539:
	s_or_b64 exec, exec, s[0:1]
	v_mov_b32_e32 v20, 0xf149f2ca
	v_mov_b32_e32 v21, 0xf149f2ca
	s_and_saveexec_b64 s[0:1], s[6:7]
	s_cbranch_execz .LBB0_1541
	v_mov_b32_e32 v97, v178
	s_mov_b32 s34, 0x3e38aa3b
	v_mov_b32_e32 v96, v22
	s_mov_b32 s35, 0x3fb8aa3b
	s_waitcnt lgkmcnt(0)
	v_pk_mul_f32 v[96:97], v[96:97], s[34:35]
	s_nop 0
	v_add_f32_e32 v21, v96, v97
.LBB0_1541:
	s_or_b64 exec, exec, s[0:1]
	s_and_saveexec_b64 s[0:1], s[8:9]
	s_cbranch_execz .LBB0_1543
	v_mov_b32_e32 v97, v179
	s_mov_b32 s34, 0x3e38aa3b
	v_mov_b32_e32 v96, v23
	s_mov_b32 s35, 0x3fb8aa3b
	s_waitcnt lgkmcnt(0)
	v_pk_mul_f32 v[22:23], v[96:97], s[34:35]
	s_nop 0
	v_add_f32_e32 v20, v22, v23
.LBB0_1543:
	s_or_b64 exec, exec, s[0:1]
	v_mov_b32_e32 v22, 0xf149f2ca
	v_mov_b32_e32 v23, 0xf149f2ca
	s_and_saveexec_b64 s[0:1], s[10:11]
	s_cbranch_execz .LBB0_1545
	v_mov_b32_e32 v97, v180
	s_mov_b32 s34, 0x3e38aa3b
	v_mov_b32_e32 v96, v16
	s_mov_b32 s35, 0x3fb8aa3b
	s_waitcnt lgkmcnt(0)
	v_pk_mul_f32 v[96:97], v[96:97], s[34:35]
	s_nop 0
	v_add_f32_e32 v23, v96, v97
.LBB0_1545:
	s_or_b64 exec, exec, s[0:1]
	s_and_saveexec_b64 s[0:1], s[12:13]
	s_cbranch_execz .LBB0_1547
	v_mov_b32_e32 v97, v181
	s_mov_b32 s34, 0x3e38aa3b
	v_mov_b32_e32 v96, v17
	s_mov_b32 s35, 0x3fb8aa3b
	s_waitcnt lgkmcnt(0)
	v_pk_mul_f32 v[16:17], v[96:97], s[34:35]
	s_nop 0
	v_add_f32_e32 v22, v16, v17
.LBB0_1547:
	s_or_b64 exec, exec, s[0:1]
	v_mov_b32_e32 v17, 0xf149f2ca
	v_mov_b32_e32 v27, 0xf149f2ca
	s_and_saveexec_b64 s[0:1], s[14:15]
	s_cbranch_execz .LBB0_1549
	v_mov_b32_e32 v97, v182
	s_mov_b32 s34, 0x3e38aa3b
	v_mov_b32_e32 v96, v18
	s_mov_b32 s35, 0x3fb8aa3b
	s_waitcnt lgkmcnt(0)
	v_pk_mul_f32 v[96:97], v[96:97], s[34:35]
	s_nop 0
	v_add_f32_e32 v27, v96, v97
.LBB0_1549:
	s_or_b64 exec, exec, s[0:1]
	s_and_saveexec_b64 s[0:1], s[16:17]
	s_cbranch_execz .LBB0_1551
	v_mov_b32_e32 v17, v183
	s_mov_b32 s34, 0x3e38aa3b
	v_mov_b32_e32 v16, v19
	s_mov_b32 s35, 0x3fb8aa3b
	s_waitcnt lgkmcnt(0)
	v_pk_mul_f32 v[16:17], v[16:17], s[34:35]
	s_nop 0
	v_add_f32_e32 v17, v16, v17
.LBB0_1551:
	s_or_b64 exec, exec, s[0:1]
	v_mov_b32_e32 v16, 0xf149f2ca
	v_mov_b32_e32 v18, 0xf149f2ca
	ds_read_b32 v176, v82 offset:1240
	ds_read_b32 v177, v83 offset:1240
	ds_read_b32 v178, v88 offset:1240
	ds_read_b32 v179, v90 offset:1240
	ds_read_b32 v180, v91 offset:1240
	ds_read_b32 v181, v92 offset:1240
	ds_read_b32 v182, v93 offset:1240
	ds_read_b32 v183, v94 offset:1240
	s_waitcnt lgkmcnt(0)
	s_and_saveexec_b64 s[0:1], vcc
	s_cbranch_execz .LBB0_1553
	v_mov_b32_e32 v19, v176
	s_mov_b32 s34, 0x3e38aa3b
	v_mov_b32_e32 v18, v12
	s_mov_b32 s35, 0x3fb8aa3b
	s_waitcnt lgkmcnt(0)
	v_pk_mul_f32 v[18:19], v[18:19], s[34:35]
	s_nop 0
	v_add_f32_e32 v18, v18, v19
.LBB0_1553:
	s_or_b64 exec, exec, s[0:1]
	s_and_saveexec_b64 s[0:1], s[4:5]
	s_cbranch_execz .LBB0_1555
	v_mov_b32_e32 v83, v177
	s_mov_b32 s4, 0x3e38aa3b
	v_mov_b32_e32 v82, v13
	s_mov_b32 s5, 0x3fb8aa3b
	s_waitcnt lgkmcnt(0)
	v_pk_mul_f32 v[12:13], v[82:83], s[4:5]
	s_nop 0
	v_add_f32_e32 v16, v12, v13
.LBB0_1555:
	s_or_b64 exec, exec, s[0:1]
	v_mov_b32_e32 v12, 0xf149f2ca
	v_mov_b32_e32 v13, 0xf149f2ca
	s_and_saveexec_b64 s[0:1], s[6:7]
	s_cbranch_execz .LBB0_1557
	v_mov_b32_e32 v83, v178
	s_mov_b32 s4, 0x3e38aa3b
	v_mov_b32_e32 v82, v14
	s_mov_b32 s5, 0x3fb8aa3b
	s_waitcnt lgkmcnt(0)
	v_pk_mul_f32 v[82:83], v[82:83], s[4:5]
	s_nop 0
	v_add_f32_e32 v13, v82, v83
.LBB0_1557:
	s_or_b64 exec, exec, s[0:1]
	s_and_saveexec_b64 s[0:1], s[8:9]
	s_cbranch_execz .LBB0_1559
	v_mov_b32_e32 v83, v179
	s_mov_b32 s4, 0x3e38aa3b
	v_mov_b32_e32 v82, v15
	s_mov_b32 s5, 0x3fb8aa3b
	s_waitcnt lgkmcnt(0)
	v_pk_mul_f32 v[14:15], v[82:83], s[4:5]
	s_nop 0
	v_add_f32_e32 v12, v14, v15
.LBB0_1559:
	s_or_b64 exec, exec, s[0:1]
	v_mov_b32_e32 v14, 0xf149f2ca
	v_mov_b32_e32 v15, 0xf149f2ca
	s_and_saveexec_b64 s[0:1], s[10:11]
	s_cbranch_execz .LBB0_1561
	v_mov_b32_e32 v83, v180
	s_mov_b32 s4, 0x3e38aa3b
	v_mov_b32_e32 v82, v8
	s_mov_b32 s5, 0x3fb8aa3b
	s_waitcnt lgkmcnt(0)
	v_pk_mul_f32 v[82:83], v[82:83], s[4:5]
	s_nop 0
	v_add_f32_e32 v15, v82, v83
.LBB0_1561:
	s_or_b64 exec, exec, s[0:1]
	s_and_saveexec_b64 s[0:1], s[12:13]
	s_cbranch_execz .LBB0_1563
	v_mov_b32_e32 v83, v181
	s_mov_b32 s4, 0x3e38aa3b
	v_mov_b32_e32 v82, v9
	s_mov_b32 s5, 0x3fb8aa3b
	s_waitcnt lgkmcnt(0)
	v_pk_mul_f32 v[8:9], v[82:83], s[4:5]
	s_nop 0
	v_add_f32_e32 v14, v8, v9
.LBB0_1563:
	s_or_b64 exec, exec, s[0:1]
	v_mov_b32_e32 v8, 0xf149f2ca
	v_mov_b32_e32 v9, 0xf149f2ca
	s_and_saveexec_b64 s[0:1], s[14:15]
	s_cbranch_execz .LBB0_1565
	v_mov_b32_e32 v83, v182
	s_mov_b32 s4, 0x3e38aa3b
	v_mov_b32_e32 v82, v10
	s_mov_b32 s5, 0x3fb8aa3b
	s_waitcnt lgkmcnt(0)
	v_pk_mul_f32 v[82:83], v[82:83], s[4:5]
	s_nop 0
	v_add_f32_e32 v9, v82, v83
.LBB0_1565:
	s_or_b64 exec, exec, s[0:1]
	s_and_saveexec_b64 s[0:1], s[16:17]
	s_cbranch_execz .LBB0_1567
	v_mov_b32_e32 v83, v183
	s_mov_b32 s4, 0x3e38aa3b
	v_mov_b32_e32 v82, v11
	s_mov_b32 s5, 0x3fb8aa3b
	s_waitcnt lgkmcnt(0)
	v_pk_mul_f32 v[10:11], v[82:83], s[4:5]
	s_nop 0
	v_add_f32_e32 v8, v10, v11

.LBB0_1596:
	s_or_b64 exec, exec, s[0:1]
	v_mov_b32_e32 v66, 0xf149f2ca
	v_mov_b32_e32 v67, 0xf149f2ca
	ds_read_b32 v176, v88 offset:496
	ds_read_b32 v177, v89 offset:496
	ds_read_b32 v178, v90 offset:496
	ds_read_b32 v179, v91 offset:496
	ds_read_b32 v180, v93 offset:496
	ds_read_b32 v181, v94 offset:496
	ds_read_b32 v182, v95 offset:496
	ds_read_b32 v183, v96 offset:496
	s_waitcnt lgkmcnt(0)
	s_and_saveexec_b64 s[0:1], vcc
	s_cbranch_execz .LBB0_1598
	v_mov_b32_e32 v99, v176
	s_mov_b32 s34, 0x3e38aa3b
	v_mov_b32_e32 v98, v60
	s_mov_b32 s35, 0x3fb8aa3b
	s_waitcnt lgkmcnt(0)
	v_pk_mul_f32 v[98:99], v[98:99], s[34:35]
	s_nop 0
	v_add_f32_e32 v67, v98, v99
.LBB0_1598:
	s_or_b64 exec, exec, s[0:1]
	s_and_saveexec_b64 s[0:1], s[8:9]
	s_cbranch_execz .LBB0_1600
	v_mov_b32_e32 v99, v177
	s_mov_b32 s34, 0x3e38aa3b
	v_mov_b32_e32 v98, v61
	s_mov_b32 s35, 0x3fb8aa3b
	s_waitcnt lgkmcnt(0)
	v_pk_mul_f32 v[60:61], v[98:99], s[34:35]
	s_nop 0
	v_add_f32_e32 v66, v60, v61
.LBB0_1600:
	s_or_b64 exec, exec, s[0:1]
	v_mov_b32_e32 v60, 0xf149f2ca
	v_mov_b32_e32 v61, 0xf149f2ca
	s_and_saveexec_b64 s[0:1], s[10:11]
	s_cbranch_execz .LBB0_1602
	v_mov_b32_e32 v99, v178
	s_mov_b32 s34, 0x3e38aa3b
	v_mov_b32_e32 v98, v62
	s_mov_b32 s35, 0x3fb8aa3b
	s_waitcnt lgkmcnt(0)
	v_pk_mul_f32 v[98:99], v[98:99], s[34:35]
	s_nop 0
	v_add_f32_e32 v61, v98, v99
.LBB0_1602:
	s_or_b64 exec, exec, s[0:1]
	s_and_saveexec_b64 s[0:1], s[12:13]
	s_cbranch_execz .LBB0_1604
	v_mov_b32_e32 v99, v179
	s_mov_b32 s34, 0x3e38aa3b
	v_mov_b32_e32 v98, v63
	s_mov_b32 s35, 0x3fb8aa3b
	s_waitcnt lgkmcnt(0)
	v_pk_mul_f32 v[62:63], v[98:99], s[34:35]
	s_nop 0
	v_add_f32_e32 v60, v62, v63
.LBB0_1604:
	s_or_b64 exec, exec, s[0:1]
	v_mov_b32_e32 v62, 0xf149f2ca
	v_mov_b32_e32 v63, 0xf149f2ca
	s_and_saveexec_b64 s[0:1], s[14:15]
	s_cbranch_execz .LBB0_1606
	v_mov_b32_e32 v99, v180
	s_mov_b32 s34, 0x3e38aa3b
	v_mov_b32_e32 v98, v56
	s_mov_b32 s35, 0x3fb8aa3b
	s_waitcnt lgkmcnt(0)
	v_pk_mul_f32 v[98:99], v[98:99], s[34:35]
	s_nop 0
	v_add_f32_e32 v63, v98, v99
.LBB0_1606:
	s_or_b64 exec, exec, s[0:1]
	s_and_saveexec_b64 s[0:1], s[16:17]
	s_cbranch_execz .LBB0_1608
	v_mov_b32_e32 v99, v181
	s_mov_b32 s34, 0x3e38aa3b
	v_mov_b32_e32 v98, v57
	s_mov_b32 s35, 0x3fb8aa3b
	s_waitcnt lgkmcnt(0)
	v_pk_mul_f32 v[56:57], v[98:99], s[34:35]
	s_nop 0
	v_add_f32_e32 v62, v56, v57
.LBB0_1608:
	s_or_b64 exec, exec, s[0:1]
	v_mov_b32_e32 v56, 0xf149f2ca
	v_mov_b32_e32 v92, 0xf149f2ca
	s_and_saveexec_b64 s[0:1], s[18:19]
	s_cbranch_execz .LBB0_1610
	v_mov_b32_e32 v99, v182
	s_mov_b32 s34, 0x3e38aa3b
	v_mov_b32_e32 v98, v58
	s_mov_b32 s35, 0x3fb8aa3b
	s_waitcnt lgkmcnt(0)
	v_pk_mul_f32 v[98:99], v[98:99], s[34:35]
	s_nop 0
	v_add_f32_e32 v92, v98, v99
.LBB0_1610:
	s_or_b64 exec, exec, s[0:1]
	s_and_saveexec_b64 s[0:1], s[20:21]
	s_cbranch_execz .LBB0_1612
	v_mov_b32_e32 v57, v183
	s_mov_b32 s34, 0x3e38aa3b
	v_mov_b32_e32 v56, v59
	s_mov_b32 s35, 0x3fb8aa3b
	s_waitcnt lgkmcnt(0)
	v_pk_mul_f32 v[56:57], v[56:57], s[34:35]
	s_nop 0
	v_add_f32_e32 v56, v56, v57
.LBB0_1612:
	s_or_b64 exec, exec, s[0:1]
	v_mov_b32_e32 v57, 0xf149f2ca
	v_mov_b32_e32 v58, 0xf149f2ca
	ds_read_b32 v176, v88 offset:620
	ds_read_b32 v177, v89 offset:620
	ds_read_b32 v178, v90 offset:620
	ds_read_b32 v179, v91 offset:620
	ds_read_b32 v180, v93 offset:620
	ds_read_b32 v181, v94 offset:620
	ds_read_b32 v182, v95 offset:620
	ds_read_b32 v183, v96 offset:620
	s_waitcnt lgkmcnt(0)
	s_and_saveexec_b64 s[0:1], vcc
	s_cbranch_execz .LBB0_1614
	v_mov_b32_e32 v59, v176
	s_mov_b32 s34, 0x3e38aa3b
	v_mov_b32_e32 v58, v52
	s_mov_b32 s35, 0x3fb8aa3b
	s_waitcnt lgkmcnt(0)
	v_pk_mul_f32 v[58:59], v[58:59], s[34:35]
	s_nop 0
	v_add_f32_e32 v58, v58, v59
.LBB0_1614:
	s_or_b64 exec, exec, s[0:1]
	s_and_saveexec_b64 s[0:1], s[8:9]
	s_cbranch_execz .LBB0_1616
	v_mov_b32_e32 v99, v177
	s_mov_b32 s34, 0x3e38aa3b
	v_mov_b32_e32 v98, v53
	s_mov_b32 s35, 0x3fb8aa3b
	s_waitcnt lgkmcnt(0)
	v_pk_mul_f32 v[52:53], v[98:99], s[34:35]
	s_nop 0
	v_add_f32_e32 v57, v52, v53
.LBB0_1616:
	s_or_b64 exec, exec, s[0:1]
	v_mov_b32_e32 v52, 0xf149f2ca
	v_mov_b32_e32 v53, 0xf149f2ca
	s_and_saveexec_b64 s[0:1], s[10:11]
	s_cbranch_execz .LBB0_1618
	v_mov_b32_e32 v99, v178
	s_mov_b32 s34, 0x3e38aa3b
	v_mov_b32_e32 v98, v54
	s_mov_b32 s35, 0x3fb8aa3b
	s_waitcnt lgkmcnt(0)
	v_pk_mul_f32 v[98:99], v[98:99], s[34:35]
	s_nop 0
	v_add_f32_e32 v53, v98, v99
.LBB0_1618:
	s_or_b64 exec, exec, s[0:1]
	s_and_saveexec_b64 s[0:1], s[12:13]
	s_cbranch_execz .LBB0_1620
	v_mov_b32_e32 v99, v179
	s_mov_b32 s34, 0x3e38aa3b
	v_mov_b32_e32 v98, v55
	s_mov_b32 s35, 0x3fb8aa3b
	s_waitcnt lgkmcnt(0)
	v_pk_mul_f32 v[54:55], v[98:99], s[34:35]
	s_nop 0
	v_add_f32_e32 v52, v54, v55
.LBB0_1620:
	s_or_b64 exec, exec, s[0:1]
	v_mov_b32_e32 v54, 0xf149f2ca
	v_mov_b32_e32 v55, 0xf149f2ca
	s_and_saveexec_b64 s[0:1], s[14:15]
	s_cbranch_execz .LBB0_1622
	v_mov_b32_e32 v99, v180
	s_mov_b32 s34, 0x3e38aa3b
	v_mov_b32_e32 v98, v48
	s_mov_b32 s35, 0x3fb8aa3b
	s_waitcnt lgkmcnt(0)
	v_pk_mul_f32 v[98:99], v[98:99], s[34:35]
	s_nop 0
	v_add_f32_e32 v55, v98, v99
.LBB0_1622:
	s_or_b64 exec, exec, s[0:1]
	s_and_saveexec_b64 s[0:1], s[16:17]
	s_cbranch_execz .LBB0_1624
	v_mov_b32_e32 v99, v181
	s_mov_b32 s34, 0x3e38aa3b
	v_mov_b32_e32 v98, v49
	s_mov_b32 s35, 0x3fb8aa3b
	s_waitcnt lgkmcnt(0)
	v_pk_mul_f32 v[48:49], v[98:99], s[34:35]
	s_nop 0
	v_add_f32_e32 v54, v48, v49
.LBB0_1624:
	s_or_b64 exec, exec, s[0:1]
	v_mov_b32_e32 v48, 0xf149f2ca
	v_mov_b32_e32 v59, 0xf149f2ca
	s_and_saveexec_b64 s[0:1], s[18:19]
	s_cbranch_execz .LBB0_1626
	v_mov_b32_e32 v99, v182
	s_mov_b32 s34, 0x3e38aa3b
	v_mov_b32_e32 v98, v50
	s_mov_b32 s35, 0x3fb8aa3b
	s_waitcnt lgkmcnt(0)
	v_pk_mul_f32 v[98:99], v[98:99], s[34:35]
	s_nop 0
	v_add_f32_e32 v59, v98, v99
.LBB0_1626:
	s_or_b64 exec, exec, s[0:1]
	s_and_saveexec_b64 s[0:1], s[20:21]
	s_cbranch_execz .LBB0_1628
	v_mov_b32_e32 v49, v183
	s_mov_b32 s34, 0x3e38aa3b
	v_mov_b32_e32 v48, v51
	s_mov_b32 s35, 0x3fb8aa3b
	s_waitcnt lgkmcnt(0)
	v_pk_mul_f32 v[48:49], v[48:49], s[34:35]
	s_nop 0
	v_add_f32_e32 v48, v48, v49
.LBB0_1628:
	s_or_b64 exec, exec, s[0:1]
	v_mov_b32_e32 v49, 0xf149f2ca
	v_mov_b32_e32 v50, 0xf149f2ca
	ds_read_b32 v176, v88 offset:744
	ds_read_b32 v177, v89 offset:744
	ds_read_b32 v178, v90 offset:744
	ds_read_b32 v179, v91 offset:744
	ds_read_b32 v180, v93 offset:744
	ds_read_b32 v181, v94 offset:744
	ds_read_b32 v182, v95 offset:744
	ds_read_b32 v183, v96 offset:744
	s_waitcnt lgkmcnt(0)
	s_and_saveexec_b64 s[0:1], vcc
	s_cbranch_execz .LBB0_1630
	v_mov_b32_e32 v51, v176
	s_mov_b32 s34, 0x3e38aa3b
	v_mov_b32_e32 v50, v44
	s_mov_b32 s35, 0x3fb8aa3b
	s_waitcnt lgkmcnt(0)
	v_pk_mul_f32 v[50:51], v[50:51], s[34:35]
	s_nop 0
	v_add_f32_e32 v50, v50, v51
.LBB0_1630:
	s_or_b64 exec, exec, s[0:1]
	s_and_saveexec_b64 s[0:1], s[8:9]
	s_cbranch_execz .LBB0_1632
	v_mov_b32_e32 v99, v177
	s_mov_b32 s34, 0x3e38aa3b
	v_mov_b32_e32 v98, v45
	s_mov_b32 s35, 0x3fb8aa3b
	s_waitcnt lgkmcnt(0)
	v_pk_mul_f32 v[44:45], v[98:99], s[34:35]
	s_nop 0
	v_add_f32_e32 v49, v44, v45
.LBB0_1632:
	s_or_b64 exec, exec, s[0:1]
	v_mov_b32_e32 v44, 0xf149f2ca
	v_mov_b32_e32 v45, 0xf149f2ca
	s_and_saveexec_b64 s[0:1], s[10:11]
	s_cbranch_execz .LBB0_1634
	v_mov_b32_e32 v99, v178
	s_mov_b32 s34, 0x3e38aa3b
	v_mov_b32_e32 v98, v46
	s_mov_b32 s35, 0x3fb8aa3b
	s_waitcnt lgkmcnt(0)
	v_pk_mul_f32 v[98:99], v[98:99], s[34:35]
	s_nop 0
	v_add_f32_e32 v45, v98, v99
.LBB0_1634:
	s_or_b64 exec, exec, s[0:1]
	s_and_saveexec_b64 s[0:1], s[12:13]
	s_cbranch_execz .LBB0_1636
	v_mov_b32_e32 v99, v179
	s_mov_b32 s34, 0x3e38aa3b
	v_mov_b32_e32 v98, v47
	s_mov_b32 s35, 0x3fb8aa3b
	s_waitcnt lgkmcnt(0)
	v_pk_mul_f32 v[46:47], v[98:99], s[34:35]
	s_nop 0
	v_add_f32_e32 v44, v46, v47
.LBB0_1636:
	s_or_b64 exec, exec, s[0:1]
	v_mov_b32_e32 v46, 0xf149f2ca
	v_mov_b32_e32 v47, 0xf149f2ca
	s_and_saveexec_b64 s[0:1], s[14:15]
	s_cbranch_execz .LBB0_1638
	v_mov_b32_e32 v99, v180
	s_mov_b32 s34, 0x3e38aa3b
	v_mov_b32_e32 v98, v40
	s_mov_b32 s35, 0x3fb8aa3b
	s_waitcnt lgkmcnt(0)
	v_pk_mul_f32 v[98:99], v[98:99], s[34:35]
	s_nop 0
	v_add_f32_e32 v47, v98, v99
.LBB0_1638:
	s_or_b64 exec, exec, s[0:1]
	s_and_saveexec_b64 s[0:1], s[16:17]
	s_cbranch_execz .LBB0_1640
	v_mov_b32_e32 v99, v181
	s_mov_b32 s34, 0x3e38aa3b
	v_mov_b32_e32 v98, v41
	s_mov_b32 s35, 0x3fb8aa3b
	s_waitcnt lgkmcnt(0)
	v_pk_mul_f32 v[40:41], v[98:99], s[34:35]
	s_nop 0
	v_add_f32_e32 v46, v40, v41
.LBB0_1640:
	s_or_b64 exec, exec, s[0:1]
	v_mov_b32_e32 v40, 0xf149f2ca
	v_mov_b32_e32 v51, 0xf149f2ca
	s_and_saveexec_b64 s[0:1], s[18:19]
	s_cbranch_execz .LBB0_1642
	v_mov_b32_e32 v99, v182
	s_mov_b32 s34, 0x3e38aa3b
	v_mov_b32_e32 v98, v42
	s_mov_b32 s35, 0x3fb8aa3b
	s_waitcnt lgkmcnt(0)
	v_pk_mul_f32 v[98:99], v[98:99], s[34:35]
	s_nop 0
	v_add_f32_e32 v51, v98, v99
.LBB0_1642:
	s_or_b64 exec, exec, s[0:1]
	s_and_saveexec_b64 s[0:1], s[20:21]
	s_cbranch_execz .LBB0_1644
	v_mov_b32_e32 v41, v183
	s_mov_b32 s34, 0x3e38aa3b
	v_mov_b32_e32 v40, v43
	s_mov_b32 s35, 0x3fb8aa3b
	s_waitcnt lgkmcnt(0)
	v_pk_mul_f32 v[40:41], v[40:41], s[34:35]
	s_nop 0
	v_add_f32_e32 v40, v40, v41
.LBB0_1644:
	s_or_b64 exec, exec, s[0:1]
	v_mov_b32_e32 v41, 0xf149f2ca
	v_mov_b32_e32 v42, 0xf149f2ca
	ds_read_b32 v176, v88 offset:868
	ds_read_b32 v177, v89 offset:868
	ds_read_b32 v178, v90 offset:868
	ds_read_b32 v179, v91 offset:868
	ds_read_b32 v180, v93 offset:868
	ds_read_b32 v181, v94 offset:868
	ds_read_b32 v182, v95 offset:868
	ds_read_b32 v183, v96 offset:868
	s_waitcnt lgkmcnt(0)
	s_and_saveexec_b64 s[0:1], vcc
	s_cbranch_execz .LBB0_1646
	v_mov_b32_e32 v43, v176
	s_mov_b32 s34, 0x3e38aa3b
	v_mov_b32_e32 v42, v36
	s_mov_b32 s35, 0x3fb8aa3b
	s_waitcnt lgkmcnt(0)
	v_pk_mul_f32 v[42:43], v[42:43], s[34:35]
	s_nop 0
	v_add_f32_e32 v42, v42, v43
.LBB0_1646:
	s_or_b64 exec, exec, s[0:1]
	s_and_saveexec_b64 s[0:1], s[8:9]
	s_cbranch_execz .LBB0_1648
	v_mov_b32_e32 v99, v177
	s_mov_b32 s34, 0x3e38aa3b
	v_mov_b32_e32 v98, v37
	s_mov_b32 s35, 0x3fb8aa3b
	s_waitcnt lgkmcnt(0)
	v_pk_mul_f32 v[36:37], v[98:99], s[34:35]
	s_nop 0
	v_add_f32_e32 v41, v36, v37
.LBB0_1648:
	s_or_b64 exec, exec, s[0:1]
	v_mov_b32_e32 v36, 0xf149f2ca
	v_mov_b32_e32 v37, 0xf149f2ca
	s_and_saveexec_b64 s[0:1], s[10:11]
	s_cbranch_execz .LBB0_1650
	v_mov_b32_e32 v99, v178
	s_mov_b32 s34, 0x3e38aa3b
	v_mov_b32_e32 v98, v38
	s_mov_b32 s35, 0x3fb8aa3b
	s_waitcnt lgkmcnt(0)
	v_pk_mul_f32 v[98:99], v[98:99], s[34:35]
	s_nop 0
	v_add_f32_e32 v37, v98, v99
.LBB0_1650:
	s_or_b64 exec, exec, s[0:1]
	s_and_saveexec_b64 s[0:1], s[12:13]
	s_cbranch_execz .LBB0_1652
	v_mov_b32_e32 v99, v179
	s_mov_b32 s34, 0x3e38aa3b
	v_mov_b32_e32 v98, v39
	s_mov_b32 s35, 0x3fb8aa3b
	s_waitcnt lgkmcnt(0)
	v_pk_mul_f32 v[38:39], v[98:99], s[34:35]
	s_nop 0
	v_add_f32_e32 v36, v38, v39
.LBB0_1652:
	s_or_b64 exec, exec, s[0:1]
	v_mov_b32_e32 v38, 0xf149f2ca
	v_mov_b32_e32 v39, 0xf149f2ca
	s_and_saveexec_b64 s[0:1], s[14:15]
	s_cbranch_execz .LBB0_1654
	v_mov_b32_e32 v99, v180
	s_mov_b32 s34, 0x3e38aa3b
	v_mov_b32_e32 v98, v32
	s_mov_b32 s35, 0x3fb8aa3b
	s_waitcnt lgkmcnt(0)
	v_pk_mul_f32 v[98:99], v[98:99], s[34:35]
	s_nop 0
	v_add_f32_e32 v39, v98, v99
.LBB0_1654:
	s_or_b64 exec, exec, s[0:1]
	s_and_saveexec_b64 s[0:1], s[16:17]
	s_cbranch_execz .LBB0_1656
	v_mov_b32_e32 v99, v181
	s_mov_b32 s34, 0x3e38aa3b
	v_mov_b32_e32 v98, v33
	s_mov_b32 s35, 0x3fb8aa3b
	s_waitcnt lgkmcnt(0)
	v_pk_mul_f32 v[32:33], v[98:99], s[34:35]
	s_nop 0
	v_add_f32_e32 v38, v32, v33
.LBB0_1656:
	s_or_b64 exec, exec, s[0:1]
	v_mov_b32_e32 v32, 0xf149f2ca
	v_mov_b32_e32 v43, 0xf149f2ca
	s_and_saveexec_b64 s[0:1], s[18:19]
	s_cbranch_execz .LBB0_1658
	v_mov_b32_e32 v99, v182
	s_mov_b32 s34, 0x3e38aa3b
	v_mov_b32_e32 v98, v34
	s_mov_b32 s35, 0x3fb8aa3b
	s_waitcnt lgkmcnt(0)
	v_pk_mul_f32 v[98:99], v[98:99], s[34:35]
	s_nop 0
	v_add_f32_e32 v43, v98, v99
.LBB0_1658:
	s_or_b64 exec, exec, s[0:1]
	s_and_saveexec_b64 s[0:1], s[20:21]
	s_cbranch_execz .LBB0_1660
	v_mov_b32_e32 v33, v183
	s_mov_b32 s34, 0x3e38aa3b
	v_mov_b32_e32 v32, v35
	s_mov_b32 s35, 0x3fb8aa3b
	s_waitcnt lgkmcnt(0)
	v_pk_mul_f32 v[32:33], v[32:33], s[34:35]
	s_nop 0
	v_add_f32_e32 v32, v32, v33
.LBB0_1660:
	s_or_b64 exec, exec, s[0:1]
	v_mov_b32_e32 v33, 0xf149f2ca
	v_mov_b32_e32 v34, 0xf149f2ca
	ds_read_b32 v176, v88 offset:992
	ds_read_b32 v177, v89 offset:992
	ds_read_b32 v178, v90 offset:992
	ds_read_b32 v179, v91 offset:992
	ds_read_b32 v180, v93 offset:992
	ds_read_b32 v181, v94 offset:992
	ds_read_b32 v182, v95 offset:992
	ds_read_b32 v183, v96 offset:992
	s_waitcnt lgkmcnt(0)
	s_and_saveexec_b64 s[0:1], vcc
	s_cbranch_execz .LBB0_1662
	v_mov_b32_e32 v35, v176
	s_mov_b32 s34, 0x3e38aa3b
	v_mov_b32_e32 v34, v28
	s_mov_b32 s35, 0x3fb8aa3b
	s_waitcnt lgkmcnt(0)
	v_pk_mul_f32 v[34:35], v[34:35], s[34:35]
	s_nop 0
	v_add_f32_e32 v34, v34, v35
.LBB0_1662:
	s_or_b64 exec, exec, s[0:1]
	s_and_saveexec_b64 s[0:1], s[8:9]
	s_cbranch_execz .LBB0_1664
	v_mov_b32_e32 v99, v177
	s_mov_b32 s34, 0x3e38aa3b
	v_mov_b32_e32 v98, v29
	s_mov_b32 s35, 0x3fb8aa3b
	s_waitcnt lgkmcnt(0)
	v_pk_mul_f32 v[28:29], v[98:99], s[34:35]
	s_nop 0
	v_add_f32_e32 v33, v28, v29
.LBB0_1664:
	s_or_b64 exec, exec, s[0:1]
	v_mov_b32_e32 v28, 0xf149f2ca
	v_mov_b32_e32 v29, 0xf149f2ca
	s_and_saveexec_b64 s[0:1], s[10:11]
	s_cbranch_execz .LBB0_1666
	v_mov_b32_e32 v99, v178
	s_mov_b32 s34, 0x3e38aa3b
	v_mov_b32_e32 v98, v30
	s_mov_b32 s35, 0x3fb8aa3b
	s_waitcnt lgkmcnt(0)
	v_pk_mul_f32 v[98:99], v[98:99], s[34:35]
	s_nop 0
	v_add_f32_e32 v29, v98, v99
.LBB0_1666:
	s_or_b64 exec, exec, s[0:1]
	s_and_saveexec_b64 s[0:1], s[12:13]
	s_cbranch_execz .LBB0_1668
	v_mov_b32_e32 v99, v179
	s_mov_b32 s34, 0x3e38aa3b
	v_mov_b32_e32 v98, v31
	s_mov_b32 s35, 0x3fb8aa3b
	s_waitcnt lgkmcnt(0)
	v_pk_mul_f32 v[30:31], v[98:99], s[34:35]
	s_nop 0
	v_add_f32_e32 v28, v30, v31
.LBB0_1668:
	s_or_b64 exec, exec, s[0:1]
	v_mov_b32_e32 v30, 0xf149f2ca
	v_mov_b32_e32 v31, 0xf149f2ca
	s_and_saveexec_b64 s[0:1], s[14:15]
	s_cbranch_execz .LBB0_1670
	v_mov_b32_e32 v99, v180
	s_mov_b32 s34, 0x3e38aa3b
	v_mov_b32_e32 v98, v24
	s_mov_b32 s35, 0x3fb8aa3b
	s_waitcnt lgkmcnt(0)
	v_pk_mul_f32 v[98:99], v[98:99], s[34:35]
	s_nop 0
	v_add_f32_e32 v31, v98, v99
.LBB0_1670:
	s_or_b64 exec, exec, s[0:1]
	s_and_saveexec_b64 s[0:1], s[16:17]
	s_cbranch_execz .LBB0_1672
	v_mov_b32_e32 v99, v181
	s_mov_b32 s34, 0x3e38aa3b
	v_mov_b32_e32 v98, v25
	s_mov_b32 s35, 0x3fb8aa3b
	s_waitcnt lgkmcnt(0)
	v_pk_mul_f32 v[24:25], v[98:99], s[34:35]
	s_nop 0
	v_add_f32_e32 v30, v24, v25
.LBB0_1672:
	s_or_b64 exec, exec, s[0:1]
	v_mov_b32_e32 v24, 0xf149f2ca
	v_mov_b32_e32 v35, 0xf149f2ca
	s_and_saveexec_b64 s[0:1], s[18:19]
	s_cbranch_execz .LBB0_1674
	v_mov_b32_e32 v99, v182
	s_mov_b32 s34, 0x3e38aa3b
	v_mov_b32_e32 v98, v26
	s_mov_b32 s35, 0x3fb8aa3b
	s_waitcnt lgkmcnt(0)
	v_pk_mul_f32 v[98:99], v[98:99], s[34:35]
	s_nop 0
	v_add_f32_e32 v35, v98, v99
.LBB0_1674:
	s_or_b64 exec, exec, s[0:1]
	s_and_saveexec_b64 s[0:1], s[20:21]
	s_cbranch_execz .LBB0_1676
	v_mov_b32_e32 v25, v183
	s_mov_b32 s34, 0x3e38aa3b
	v_mov_b32_e32 v24, v27
	s_mov_b32 s35, 0x3fb8aa3b
	s_waitcnt lgkmcnt(0)
	v_pk_mul_f32 v[24:25], v[24:25], s[34:35]
	s_nop 0
	v_add_f32_e32 v24, v24, v25
.LBB0_1676:
	s_or_b64 exec, exec, s[0:1]
	v_mov_b32_e32 v25, 0xf149f2ca
	v_mov_b32_e32 v26, 0xf149f2ca
	ds_read_b32 v176, v88 offset:1116
	ds_read_b32 v177, v89 offset:1116
	ds_read_b32 v178, v90 offset:1116
	ds_read_b32 v179, v91 offset:1116
	ds_read_b32 v180, v93 offset:1116
	ds_read_b32 v181, v94 offset:1116
	ds_read_b32 v182, v95 offset:1116
	ds_read_b32 v183, v96 offset:1116
	s_waitcnt lgkmcnt(0)
	s_and_saveexec_b64 s[0:1], vcc
	s_cbranch_execz .LBB0_1678
	v_mov_b32_e32 v27, v176
	s_mov_b32 s34, 0x3e38aa3b
	v_mov_b32_e32 v26, v20
	s_mov_b32 s35, 0x3fb8aa3b
	s_waitcnt lgkmcnt(0)
	v_pk_mul_f32 v[26:27], v[26:27], s[34:35]
	s_nop 0
	v_add_f32_e32 v26, v26, v27
.LBB0_1678:
	s_or_b64 exec, exec, s[0:1]
	s_and_saveexec_b64 s[0:1], s[8:9]
	s_cbranch_execz .LBB0_1680
	v_mov_b32_e32 v99, v177
	s_mov_b32 s34, 0x3e38aa3b
	v_mov_b32_e32 v98, v21
	s_mov_b32 s35, 0x3fb8aa3b
	s_waitcnt lgkmcnt(0)
	v_pk_mul_f32 v[20:21], v[98:99], s[34:35]
	s_nop 0
	v_add_f32_e32 v25, v20, v21
.LBB0_1680:
	s_or_b64 exec, exec, s[0:1]
	v_mov_b32_e32 v20, 0xf149f2ca
	v_mov_b32_e32 v21, 0xf149f2ca
	s_and_saveexec_b64 s[0:1], s[10:11]
	s_cbranch_execz .LBB0_1682
	v_mov_b32_e32 v99, v178
	s_mov_b32 s34, 0x3e38aa3b
	v_mov_b32_e32 v98, v22
	s_mov_b32 s35, 0x3fb8aa3b
	s_waitcnt lgkmcnt(0)
	v_pk_mul_f32 v[98:99], v[98:99], s[34:35]
	s_nop 0
	v_add_f32_e32 v21, v98, v99
.LBB0_1682:
	s_or_b64 exec, exec, s[0:1]
	s_and_saveexec_b64 s[0:1], s[12:13]
	s_cbranch_execz .LBB0_1684
	v_mov_b32_e32 v99, v179
	s_mov_b32 s34, 0x3e38aa3b
	v_mov_b32_e32 v98, v23
	s_mov_b32 s35, 0x3fb8aa3b
	s_waitcnt lgkmcnt(0)
	v_pk_mul_f32 v[22:23], v[98:99], s[34:35]
	s_nop 0
	v_add_f32_e32 v20, v22, v23
.LBB0_1684:
	s_or_b64 exec, exec, s[0:1]
	v_mov_b32_e32 v22, 0xf149f2ca
	v_mov_b32_e32 v23, 0xf149f2ca
	s_and_saveexec_b64 s[0:1], s[14:15]
	s_cbranch_execz .LBB0_1686
	v_mov_b32_e32 v99, v180
	s_mov_b32 s34, 0x3e38aa3b
	v_mov_b32_e32 v98, v16
	s_mov_b32 s35, 0x3fb8aa3b
	s_waitcnt lgkmcnt(0)
	v_pk_mul_f32 v[98:99], v[98:99], s[34:35]
	s_nop 0
	v_add_f32_e32 v23, v98, v99
.LBB0_1686:
	s_or_b64 exec, exec, s[0:1]
	s_and_saveexec_b64 s[0:1], s[16:17]
	s_cbranch_execz .LBB0_1688
	v_mov_b32_e32 v99, v181
	s_mov_b32 s34, 0x3e38aa3b
	v_mov_b32_e32 v98, v17
	s_mov_b32 s35, 0x3fb8aa3b
	s_waitcnt lgkmcnt(0)
	v_pk_mul_f32 v[16:17], v[98:99], s[34:35]
	s_nop 0
	v_add_f32_e32 v22, v16, v17
.LBB0_1688:
	s_or_b64 exec, exec, s[0:1]
	v_mov_b32_e32 v17, 0xf149f2ca
	v_mov_b32_e32 v27, 0xf149f2ca
	s_and_saveexec_b64 s[0:1], s[18:19]
	s_cbranch_execz .LBB0_1690
	v_mov_b32_e32 v99, v182
	s_mov_b32 s34, 0x3e38aa3b
	v_mov_b32_e32 v98, v18
	s_mov_b32 s35, 0x3fb8aa3b
	s_waitcnt lgkmcnt(0)
	v_pk_mul_f32 v[98:99], v[98:99], s[34:35]
	s_nop 0
	v_add_f32_e32 v27, v98, v99
.LBB0_1690:
	s_or_b64 exec, exec, s[0:1]
	s_and_saveexec_b64 s[0:1], s[20:21]
	s_cbranch_execz .LBB0_1692
	v_mov_b32_e32 v17, v183
	s_mov_b32 s34, 0x3e38aa3b
	v_mov_b32_e32 v16, v19
	s_mov_b32 s35, 0x3fb8aa3b
	s_waitcnt lgkmcnt(0)
	v_pk_mul_f32 v[16:17], v[16:17], s[34:35]
	s_nop 0
	v_add_f32_e32 v17, v16, v17
.LBB0_1692:
	s_or_b64 exec, exec, s[0:1]
	v_mov_b32_e32 v16, 0xf149f2ca
	v_mov_b32_e32 v18, 0xf149f2ca
	ds_read_b32 v176, v88 offset:1240
	ds_read_b32 v177, v89 offset:1240
	ds_read_b32 v178, v90 offset:1240
	ds_read_b32 v179, v91 offset:1240
	ds_read_b32 v180, v93 offset:1240
	ds_read_b32 v181, v94 offset:1240
	ds_read_b32 v182, v95 offset:1240
	ds_read_b32 v183, v96 offset:1240
	s_waitcnt lgkmcnt(0)
	s_and_saveexec_b64 s[0:1], vcc
	s_cbranch_execz .LBB0_1694
	v_mov_b32_e32 v19, v176
	s_mov_b32 s34, 0x3e38aa3b
	v_mov_b32_e32 v18, v12
	s_mov_b32 s35, 0x3fb8aa3b
	s_waitcnt lgkmcnt(0)
	v_pk_mul_f32 v[18:19], v[18:19], s[34:35]
	s_nop 0
	v_add_f32_e32 v18, v18, v19
.LBB0_1694:
	s_or_b64 exec, exec, s[0:1]
	s_and_saveexec_b64 s[0:1], s[8:9]
	s_cbranch_execz .LBB0_1696
	v_mov_b32_e32 v89, v177
	s_mov_b32 s8, 0x3e38aa3b
	v_mov_b32_e32 v88, v13
	s_mov_b32 s9, 0x3fb8aa3b
	s_waitcnt lgkmcnt(0)
	v_pk_mul_f32 v[12:13], v[88:89], s[8:9]
	s_nop 0
	v_add_f32_e32 v16, v12, v13
.LBB0_1696:
	s_or_b64 exec, exec, s[0:1]
	v_mov_b32_e32 v12, 0xf149f2ca
	v_mov_b32_e32 v13, 0xf149f2ca
	s_and_saveexec_b64 s[0:1], s[10:11]
	s_cbranch_execz .LBB0_1698
	v_mov_b32_e32 v89, v178
	s_mov_b32 s8, 0x3e38aa3b
	v_mov_b32_e32 v88, v14
	s_mov_b32 s9, 0x3fb8aa3b
	s_waitcnt lgkmcnt(0)
	v_pk_mul_f32 v[88:89], v[88:89], s[8:9]
	s_nop 0
	v_add_f32_e32 v13, v88, v89
.LBB0_1698:
	s_or_b64 exec, exec, s[0:1]
	s_and_saveexec_b64 s[0:1], s[12:13]
	s_cbranch_execz .LBB0_1700
	v_mov_b32_e32 v89, v179
	s_mov_b32 s8, 0x3e38aa3b
	v_mov_b32_e32 v88, v15
	s_mov_b32 s9, 0x3fb8aa3b
	s_waitcnt lgkmcnt(0)
	v_pk_mul_f32 v[14:15], v[88:89], s[8:9]
	s_nop 0
	v_add_f32_e32 v12, v14, v15
.LBB0_1700:
	s_or_b64 exec, exec, s[0:1]
	v_mov_b32_e32 v14, 0xf149f2ca
	v_mov_b32_e32 v15, 0xf149f2ca
	s_and_saveexec_b64 s[0:1], s[14:15]
	s_cbranch_execz .LBB0_1702
	v_mov_b32_e32 v89, v180
	s_mov_b32 s8, 0x3e38aa3b
	v_mov_b32_e32 v88, v8
	s_mov_b32 s9, 0x3fb8aa3b
	s_waitcnt lgkmcnt(0)
	v_pk_mul_f32 v[88:89], v[88:89], s[8:9]
	s_nop 0
	v_add_f32_e32 v15, v88, v89
.LBB0_1702:
	s_or_b64 exec, exec, s[0:1]
	s_and_saveexec_b64 s[0:1], s[16:17]
	s_cbranch_execz .LBB0_1704
	v_mov_b32_e32 v89, v181
	s_mov_b32 s8, 0x3e38aa3b
	v_mov_b32_e32 v88, v9
	s_mov_b32 s9, 0x3fb8aa3b
	s_waitcnt lgkmcnt(0)
	v_pk_mul_f32 v[8:9], v[88:89], s[8:9]
	s_nop 0
	v_add_f32_e32 v14, v8, v9
.LBB0_1704:
	s_or_b64 exec, exec, s[0:1]
	v_mov_b32_e32 v19, 0xf149f2ca
	v_mov_b32_e32 v91, 0xf149f2ca
	s_and_saveexec_b64 s[0:1], s[18:19]
	s_cbranch_execz .LBB0_1706
	v_mov_b32_e32 v9, v182
	s_mov_b32 s8, 0x3e38aa3b
	v_mov_b32_e32 v8, v10
	s_mov_b32 s9, 0x3fb8aa3b
	s_waitcnt lgkmcnt(0)
	v_pk_mul_f32 v[8:9], v[8:9], s[8:9]
	s_nop 0
	v_add_f32_e32 v91, v8, v9
.LBB0_1706:
	s_or_b64 exec, exec, s[0:1]
	s_and_saveexec_b64 s[0:1], s[20:21]
	s_cbranch_execz .LBB0_1708
	v_mov_b32_e32 v9, v183
	s_mov_b32 s8, 0x3e38aa3b
	v_mov_b32_e32 v8, v11
	s_mov_b32 s9, 0x3fb8aa3b
	s_waitcnt lgkmcnt(0)
	v_pk_mul_f32 v[8:9], v[8:9], s[8:9]
	s_nop 0
	v_add_f32_e32 v19, v8, v9
